# trim MMA-part head/tail: dedupe lgkmcnt(0), s_setprio moved outside the barrier-to-barrier MFMA window
# speedup vs baseline: 1.0380x; 1.0109x over previous
.LBB0_384:
	s_add_u32 s54, s42, 0xfffd0080
	s_addc_u32 s55, s43, -1
	s_add_i32 s70, 0, 0x10000
	v_add_u32_e32 v96, s70, v157
	ds_read_b128 v[160:163], v96
	ds_read_b128 v[164:167], v96 offset:1024
	ds_read_b128 v[168:171], v96 offset:2048
	ds_read_b128 v[172:175], v96 offset:3072
	s_cmp_eq_u32 s69, 12
	s_cselect_b32 s57, s51, s55
	s_cselect_b32 s56, s50, s54
	s_cselect_b32 s55, s49, s68
	s_cselect_b32 s54, s66, s67
	v_lshl_add_u64 v[154:155], s[42:43], 0, v[150:151]
	s_add_i32 m0, s28, 0xc000
	ds_read_b128 v[182:185], v159
	ds_read_b128 v[186:189], v159 offset:1024
	ds_read_b128 v[190:193], v159 offset:2048
	ds_read_b128 v[194:197], v159 offset:3072
	ds_read_b128 v[198:201], v159 offset:4096
	ds_read_b128 v[224:227], v159 offset:5120
	global_load_lds_dwordx4 v[154:155], off
	v_lshl_add_u64 v[154:155], s[42:43], 0, v[152:153]
	s_add_i32 m0, s28, 0xe000
	s_mov_b64 exec, s[98:99]
	global_load_lds_dwordx4 v[154:155], off
	s_mov_b64 exec, -1
	s_waitcnt lgkmcnt(8)
	s_setprio 1
	s_barrier
	s_waitcnt lgkmcnt(0)
	v_mfma_f32_16x16x32_bf16 v[134:137], v[160:163], v[182:185], v[134:137]
	v_mfma_f32_16x16x32_bf16 v[130:133], v[168:171], v[182:185], v[130:133]
	v_mfma_f32_16x16x32_bf16 v[118:121], v[160:163], v[190:193], v[118:121]
	v_mfma_f32_16x16x32_bf16 v[114:117], v[168:171], v[190:193], v[114:117]
	v_mfma_f32_16x16x32_bf16 v[102:105], v[160:163], v[198:201], v[102:105]
	v_mfma_f32_16x16x32_bf16 v[98:101], v[168:171], v[198:201], v[98:101]
	v_mfma_f32_16x16x32_bf16 v[134:137], v[164:167], v[186:189], v[134:137]
	v_mfma_f32_16x16x32_bf16 v[130:133], v[172:175], v[186:189], v[130:133]
	v_mfma_f32_16x16x32_bf16 v[118:121], v[164:167], v[194:197], v[118:121]
	v_mfma_f32_16x16x32_bf16 v[114:117], v[172:175], v[194:197], v[114:117]
	v_mfma_f32_16x16x32_bf16 v[102:105], v[164:167], v[224:227], v[102:105]
	v_mfma_f32_16x16x32_bf16 v[98:101], v[172:175], v[224:227], v[98:101]
	s_barrier
	s_setprio 0
	s_add_i32 s72, 0, 0x14000
	s_add_i32 s70, s70, s18
	v_add_u32_e32 v96, s72, v157
	v_lshl_add_u64 v[154:155], s[54:55], 0, v[142:143]
	s_mov_b32 m0, s70
	ds_read_b128 v[228:231], v96
	ds_read_b128 v[232:235], v96 offset:1024
	ds_read_b128 v[236:239], v96 offset:2048
	ds_read_b128 v[240:243], v96 offset:3072
	global_load_lds_dwordx4 v[154:155], off
	v_lshl_add_u64 v[176:177], s[54:55], 0, v[138:139]
	s_add_i32 m0, s70, 0x2000
	s_nop 0
	global_load_lds_dwordx4 v[176:177], off
	s_setprio 1
	s_barrier
	s_waitcnt lgkmcnt(0)
	v_mfma_f32_16x16x32_bf16 v[126:129], v[228:231], v[182:185], v[126:129]
	v_mfma_f32_16x16x32_bf16 v[122:125], v[236:239], v[182:185], v[122:125]
	v_mfma_f32_16x16x32_bf16 v[110:113], v[228:231], v[190:193], v[110:113]
	s_mov_b32 m0, s28
	v_mfma_f32_16x16x32_bf16 v[106:109], v[236:239], v[190:193], v[106:109]
	v_lshl_add_u64 v[202:203], s[56:57], 0, v[144:145]
	v_mfma_f32_16x16x32_bf16 v[92:95], v[228:231], v[198:201], v[92:95]
	v_mfma_f32_16x16x32_bf16 v[88:91], v[236:239], v[198:201], v[88:91]
	v_mfma_f32_16x16x32_bf16 v[126:129], v[232:235], v[186:189], v[126:129]
	v_mfma_f32_16x16x32_bf16 v[122:125], v[240:243], v[186:189], v[122:125]
	v_mfma_f32_16x16x32_bf16 v[110:113], v[232:235], v[194:197], v[110:113]
	v_mfma_f32_16x16x32_bf16 v[106:109], v[240:243], v[194:197], v[106:109]
	v_mfma_f32_16x16x32_bf16 v[92:95], v[232:235], v[224:227], v[92:95]
	v_mfma_f32_16x16x32_bf16 v[88:91], v[240:243], v[224:227], v[88:91]
	s_barrier
	s_setprio 0
	ds_read_b128 v[182:185], v159 offset:16384
	ds_read_b128 v[186:189], v159 offset:17408
	ds_read_b128 v[190:193], v159 offset:18432
	ds_read_b128 v[194:197], v159 offset:19456
	ds_read_b128 v[198:201], v159 offset:20480
	ds_read_b128 v[224:227], v159 offset:21504
	global_load_lds_dwordx4 v[202:203], off
	v_lshl_add_u64 v[244:245], s[56:57], 0, v[140:141]
	s_mov_b32 m0, s37
	s_mov_b64 exec, s[98:99]
	global_load_lds_dwordx4 v[244:245], off
	s_mov_b64 exec, -1
	s_setprio 1
	s_barrier
	s_waitcnt lgkmcnt(0)
	v_mfma_f32_16x16x32_bf16 v[84:87], v[160:163], v[182:185], v[84:87]
	v_mfma_f32_16x16x32_bf16 v[80:83], v[168:171], v[182:185], v[80:83]
	v_mfma_f32_16x16x32_bf16 v[68:71], v[160:163], v[190:193], v[68:71]
	v_mfma_f32_16x16x32_bf16 v[64:67], v[168:171], v[190:193], v[64:67]
	v_mfma_f32_16x16x32_bf16 v[28:31], v[160:163], v[198:201], v[28:31]
	v_mfma_f32_16x16x32_bf16 v[24:27], v[168:171], v[198:201], v[24:27]
	v_mfma_f32_16x16x32_bf16 v[84:87], v[164:167], v[186:189], v[84:87]
	v_mfma_f32_16x16x32_bf16 v[80:83], v[172:175], v[186:189], v[80:83]
	v_mfma_f32_16x16x32_bf16 v[68:71], v[164:167], v[194:197], v[68:71]
	v_mfma_f32_16x16x32_bf16 v[64:67], v[172:175], v[194:197], v[64:67]
	v_mfma_f32_16x16x32_bf16 v[28:31], v[164:167], v[224:227], v[28:31]
	v_mfma_f32_16x16x32_bf16 v[24:27], v[172:175], v[224:227], v[24:27]
	s_barrier
	s_setprio 0
	s_add_u32 s70, s54, 0x40000
	s_addc_u32 s71, s55, 0
	s_add_i32 s72, s72, s18
	v_lshl_add_u64 v[160:161], s[70:71], 0, v[142:143]
	s_mov_b32 m0, s72
	s_nop 0
	global_load_lds_dwordx4 v[160:161], off
	v_lshl_add_u64 v[160:161], s[70:71], 0, v[138:139]
	s_add_i32 m0, s72, 0x2000
	s_nop 0
	global_load_lds_dwordx4 v[160:161], off
	s_waitcnt vmcnt(6)
	s_setprio 1
	s_barrier
	v_mfma_f32_16x16x32_bf16 v[76:79], v[228:231], v[182:185], v[76:79]
	v_mfma_f32_16x16x32_bf16 v[72:75], v[236:239], v[182:185], v[72:75]
	v_mfma_f32_16x16x32_bf16 v[60:63], v[228:231], v[190:193], v[60:63]
	s_add_i32 s70, 0, 0x18000
	v_mfma_f32_16x16x32_bf16 v[56:59], v[236:239], v[190:193], v[56:59]
	v_add_u32_e32 v96, s70, v157
	v_mfma_f32_16x16x32_bf16 v[20:23], v[228:231], v[198:201], v[20:23]
	v_mfma_f32_16x16x32_bf16 v[16:19], v[236:239], v[198:201], v[16:19]
	v_mfma_f32_16x16x32_bf16 v[76:79], v[232:235], v[186:189], v[76:79]
	v_mfma_f32_16x16x32_bf16 v[72:75], v[240:243], v[186:189], v[72:75]
	v_mfma_f32_16x16x32_bf16 v[60:63], v[232:235], v[194:197], v[60:63]
	v_mfma_f32_16x16x32_bf16 v[56:59], v[240:243], v[194:197], v[56:59]
	v_mfma_f32_16x16x32_bf16 v[20:23], v[232:235], v[224:227], v[20:23]
	v_mfma_f32_16x16x32_bf16 v[16:19], v[240:243], v[224:227], v[16:19]
	s_barrier
	s_setprio 0
	ds_read_b128 v[160:163], v96
	ds_read_b128 v[164:167], v96 offset:1024
	ds_read_b128 v[168:171], v96 offset:2048
	ds_read_b128 v[172:175], v96 offset:3072
	s_add_u32 s56, s56, 0x30000
	s_addc_u32 s57, s57, 0
	s_mov_b32 m0, s58
	v_lshl_add_u64 v[228:229], s[56:57], 0, v[144:145]
	ds_read_b128 v[182:185], v159 offset:32768
	ds_read_b128 v[186:189], v159 offset:33792
	ds_read_b128 v[190:193], v159 offset:34816
	ds_read_b128 v[194:197], v159 offset:35840
	ds_read_b128 v[198:201], v159 offset:36864
	ds_read_b128 v[224:227], v159 offset:37888
	global_load_lds_dwordx4 v[228:229], off
	v_lshl_add_u64 v[228:229], s[56:57], 0, v[140:141]
	s_mov_b32 m0, s59
	s_mov_b64 exec, s[98:99]
	global_load_lds_dwordx4 v[228:229], off
	s_mov_b64 exec, -1
	s_waitcnt lgkmcnt(8)
	s_setprio 1
	s_barrier
	s_waitcnt lgkmcnt(0)
	v_mfma_f32_16x16x32_bf16 v[134:137], v[160:163], v[182:185], v[134:137]
	v_mfma_f32_16x16x32_bf16 v[130:133], v[168:171], v[182:185], v[130:133]
	v_mfma_f32_16x16x32_bf16 v[118:121], v[160:163], v[190:193], v[118:121]
	v_mfma_f32_16x16x32_bf16 v[114:117], v[168:171], v[190:193], v[114:117]
	v_mfma_f32_16x16x32_bf16 v[102:105], v[160:163], v[198:201], v[102:105]
	v_mfma_f32_16x16x32_bf16 v[98:101], v[168:171], v[198:201], v[98:101]
	v_mfma_f32_16x16x32_bf16 v[134:137], v[164:167], v[186:189], v[134:137]
	v_mfma_f32_16x16x32_bf16 v[130:133], v[172:175], v[186:189], v[130:133]
	v_mfma_f32_16x16x32_bf16 v[118:121], v[164:167], v[194:197], v[118:121]
	v_mfma_f32_16x16x32_bf16 v[114:117], v[172:175], v[194:197], v[114:117]
	v_mfma_f32_16x16x32_bf16 v[102:105], v[164:167], v[224:227], v[102:105]
	v_mfma_f32_16x16x32_bf16 v[98:101], v[172:175], v[224:227], v[98:101]
	s_barrier
	s_setprio 0
	s_add_i32 s56, 0, 0x1c000
	s_add_i32 s57, s70, s18
	v_add_u32_e32 v96, s56, v157
	v_lshl_add_u64 v[154:155], v[154:155], 0, s[6:7]
	s_mov_b32 m0, s57
	ds_read_b128 v[228:231], v96
	ds_read_b128 v[232:235], v96 offset:1024
	ds_read_b128 v[236:239], v96 offset:2048
	ds_read_b128 v[240:243], v96 offset:3072
	global_load_lds_dwordx4 v[154:155], off
	v_lshl_add_u64 v[154:155], v[176:177], 0, s[6:7]
	s_add_i32 m0, s57, 0x2000
	s_nop 0
	global_load_lds_dwordx4 v[154:155], off
	s_setprio 1
	s_barrier
	s_waitcnt lgkmcnt(0)
	v_mfma_f32_16x16x32_bf16 v[126:129], v[228:231], v[182:185], v[126:129]
	v_mfma_f32_16x16x32_bf16 v[122:125], v[236:239], v[182:185], v[122:125]
	v_mfma_f32_16x16x32_bf16 v[110:113], v[228:231], v[190:193], v[110:113]
	s_mov_b32 m0, s60
	v_mfma_f32_16x16x32_bf16 v[106:109], v[236:239], v[190:193], v[106:109]
	v_lshl_add_u64 v[154:155], v[202:203], 0, s[6:7]
	v_mfma_f32_16x16x32_bf16 v[92:95], v[228:231], v[198:201], v[92:95]
	v_mfma_f32_16x16x32_bf16 v[88:91], v[236:239], v[198:201], v[88:91]
	v_mfma_f32_16x16x32_bf16 v[126:129], v[232:235], v[186:189], v[126:129]
	v_mfma_f32_16x16x32_bf16 v[122:125], v[240:243], v[186:189], v[122:125]
	v_mfma_f32_16x16x32_bf16 v[110:113], v[232:235], v[194:197], v[110:113]
	v_mfma_f32_16x16x32_bf16 v[106:109], v[240:243], v[194:197], v[106:109]
	v_mfma_f32_16x16x32_bf16 v[92:95], v[232:235], v[224:227], v[92:95]
	v_mfma_f32_16x16x32_bf16 v[88:91], v[240:243], v[224:227], v[88:91]
	s_barrier
	s_setprio 0
	ds_read_b128 v[182:185], v159 offset:49152
	ds_read_b128 v[186:189], v159 offset:50176
	ds_read_b128 v[190:193], v159 offset:51200
	ds_read_b128 v[194:197], v159 offset:52224
	ds_read_b128 v[198:201], v159 offset:53248
	ds_read_b128 v[224:227], v159 offset:54272
	global_load_lds_dwordx4 v[154:155], off
	v_lshl_add_u64 v[154:155], v[244:245], 0, s[6:7]
	s_mov_b32 m0, s61
	s_mov_b64 exec, s[98:99]
	global_load_lds_dwordx4 v[154:155], off
	s_mov_b64 exec, -1
	s_setprio 1
	s_barrier
	s_waitcnt lgkmcnt(0)
	v_mfma_f32_16x16x32_bf16 v[84:87], v[160:163], v[182:185], v[84:87]
	v_mfma_f32_16x16x32_bf16 v[80:83], v[168:171], v[182:185], v[80:83]
	v_mfma_f32_16x16x32_bf16 v[68:71], v[160:163], v[190:193], v[68:71]
	v_mfma_f32_16x16x32_bf16 v[64:67], v[168:171], v[190:193], v[64:67]
	v_mfma_f32_16x16x32_bf16 v[28:31], v[160:163], v[198:201], v[28:31]
	v_mfma_f32_16x16x32_bf16 v[24:27], v[168:171], v[198:201], v[24:27]
	v_mfma_f32_16x16x32_bf16 v[84:87], v[164:167], v[186:189], v[84:87]
	v_mfma_f32_16x16x32_bf16 v[80:83], v[172:175], v[186:189], v[80:83]
	v_mfma_f32_16x16x32_bf16 v[68:71], v[164:167], v[194:197], v[68:71]
	v_mfma_f32_16x16x32_bf16 v[64:67], v[172:175], v[194:197], v[64:67]
	v_mfma_f32_16x16x32_bf16 v[28:31], v[164:167], v[224:227], v[28:31]
	v_mfma_f32_16x16x32_bf16 v[24:27], v[172:175], v[224:227], v[24:27]
	s_barrier
	s_setprio 0
	s_add_u32 s54, s54, 0x40080
	s_addc_u32 s55, s55, 0
	s_add_i32 s56, s56, s18
	v_lshl_add_u64 v[154:155], s[54:55], 0, v[142:143]
	s_mov_b32 m0, s56
	s_nop 0
	global_load_lds_dwordx4 v[154:155], off
	v_lshl_add_u64 v[154:155], s[54:55], 0, v[138:139]
	s_add_i32 m0, s56, 0x2000
	s_nop 0
	global_load_lds_dwordx4 v[154:155], off
	s_waitcnt vmcnt(6)
	s_setprio 1
	s_barrier
	v_mfma_f32_16x16x32_bf16 v[76:79], v[228:231], v[182:185], v[76:79]
	v_mfma_f32_16x16x32_bf16 v[72:75], v[236:239], v[182:185], v[72:75]
	v_mfma_f32_16x16x32_bf16 v[60:63], v[228:231], v[190:193], v[60:63]
	s_add_i32 s69, s69, 2
	v_mfma_f32_16x16x32_bf16 v[56:59], v[236:239], v[190:193], v[56:59]
	s_add_u32 s42, s42, 0x100
	v_mfma_f32_16x16x32_bf16 v[20:23], v[228:231], v[198:201], v[20:23]
	s_addc_u32 s43, s43, 0
	v_mfma_f32_16x16x32_bf16 v[16:19], v[236:239], v[198:201], v[16:19]
	s_add_u32 s67, s67, 0x100
	v_mfma_f32_16x16x32_bf16 v[76:79], v[232:235], v[186:189], v[76:79]
	s_addc_u32 s68, s68, 0
	v_mfma_f32_16x16x32_bf16 v[72:75], v[240:243], v[186:189], v[72:75]
	s_cmp_gt_u32 s69, 13
	v_mfma_f32_16x16x32_bf16 v[60:63], v[232:235], v[194:197], v[60:63]
	v_mfma_f32_16x16x32_bf16 v[56:59], v[240:243], v[194:197], v[56:59]
	v_mfma_f32_16x16x32_bf16 v[20:23], v[232:235], v[224:227], v[20:23]
	v_mfma_f32_16x16x32_bf16 v[16:19], v[240:243], v[224:227], v[16:19]
	s_barrier
	s_setprio 0
	s_cbranch_scc0 .LBB0_384
	s_waitcnt vmcnt(0)
	v_add_f32_e32 v52, v52, v53
	v_add_f32_e32 v53, v54, v55
	v_add_f32_e32 v52, v52, v53
	v_mov_b32_e32 v53, v52
	s_nop 1
	v_permlane16_swap_b32_e32 v52, v53
	v_add_f32_e32 v52, v52, v53
	v_mov_b32_e32 v53, v52
	s_nop 1
	v_permlane32_swap_b32_e32 v52, v53
	v_add_f32_e32 v52, v52, v53
	v_fmamk_f32 v52, v52, 0x3a800000, v207
	s_mul_i32 s42, s65, 0xc0
	v_rsq_f32_e32 v52, v52
	v_add_f32_e32 v36, v36, v37
	v_add_f32_e32 v37, v38, v39
	s_add_i32 s42, s42, s19
	v_add_f32_e32 v44, v44, v45
	v_add_f32_e32 v45, v46, v47
	v_add_f32_e32 v36, v36, v37
	s_cmpk_lt_u32 s42, 0x2000
	v_add_f32_e32 v44, v44, v45
	v_mov_b32_e32 v37, v36
	v_lshl_or_b32 v154, s64, 8, v158
	s_cselect_b32 s43, 1, 2
	v_or_b32_e32 v160, s42, v156
	v_mov_b32_e32 v45, v44
	v_permlane16_swap_b32_e32 v36, v37
	v_add_f32_e32 v32, v32, v33
	v_add_f32_e32 v33, v34, v35
	v_mov_b64_e32 v[34:35], s[46:47]
	v_mov_b32_e32 v96, s43
	v_permlane16_swap_b32_e32 v44, v45
	v_add_f32_e32 v38, v36, v37
	v_add_f32_e32 v36, v40, v41
	v_add_f32_e32 v37, v42, v43
	v_ashrrev_i32_e32 v155, 31, v154
	v_mad_i64_i32 v[34:35], s[42:43], v160, s25, v[34:35]
	v_pk_fma_f32 v[42:43], v[136:137], v[52:53], v[6:7] op_sel_hi:[1,0,1]
	v_pk_fma_f32 v[40:41], v[134:135], v[52:53], v[4:5] op_sel_hi:[1,0,1]
	v_add_f32_e32 v46, v44, v45
	v_add_f32_e32 v44, v48, v49
	v_add_f32_e32 v45, v50, v51
	v_lshl_add_u64 v[34:35], v[154:155], 1, v[34:35]
	v_pk_fma_f32 v[48:49], v[132:133], v[52:53], v[2:3] op_sel_hi:[1,0,1]
	v_pk_fma_f32 v[50:51], v[130:131], v[52:53], v[0:1] op_sel_hi:[1,0,1]
	v_cvt_pk_bf16_f32 v40, v40, v41
	v_cvt_pk_bf16_f32 v41, v42, v43
	v_add_f32_e32 v44, v44, v45
	v_cvt_pk_bf16_f32 v42, v50, v51
	v_cvt_pk_bf16_f32 v43, v48, v49
	v_add_f32_e32 v36, v36, v37
	v_add_f32_e32 v32, v32, v33
	global_store_dwordx4 v[34:35], v[40:43], off
	v_cmp_lt_i32_e32 vcc, s23, v160
	v_mov_b32_e32 v45, v44
	v_pk_fma_f32 v[42:43], v[128:129], v[52:53], v[14:15] op_sel_hi:[1,0,1]
	v_pk_fma_f32 v[40:41], v[126:127], v[52:53], v[12:13] op_sel_hi:[1,0,1]
	v_mov_b32_e32 v37, v36
	v_mov_b32_e32 v33, v32
	v_pk_fma_f32 v[48:49], v[124:125], v[52:53], v[10:11] op_sel_hi:[1,0,1]
	v_pk_fma_f32 v[50:51], v[122:123], v[52:53], v[8:9] op_sel_hi:[1,0,1]
	v_cvt_pk_bf16_f32 v40, v40, v41
	v_cvt_pk_bf16_f32 v41, v42, v43
	v_cndmask_b32_e32 v96, 0, v96, vcc
	v_cvt_pk_bf16_f32 v42, v50, v51
	v_cvt_pk_bf16_f32 v43, v48, v49
	global_store_dwordx4 v[34:35], v[40:43], off offset:256
	v_add_u32_e32 v34, 16, v160
	v_permlane16_swap_b32_e32 v44, v45
	v_permlane16_swap_b32_e32 v36, v37
	v_permlane16_swap_b32_e32 v32, v33
	v_cmp_gt_u32_e32 vcc, s24, v34
	v_add_f32_e32 v44, v44, v45
	v_add_f32_e32 v36, v36, v37
	v_add_f32_e32 v32, v32, v33
	v_cndmask_b32_e64 v35, 2, 1, vcc
	v_cmp_lt_i32_e32 vcc, s26, v160
	v_mov_b32_e32 v47, v46
	v_mov_b32_e32 v45, v44
	v_mov_b32_e32 v39, v38
	v_mov_b32_e32 v37, v36
	v_mov_b32_e32 v33, v32
	v_cndmask_b32_e32 v35, 0, v35, vcc
	v_permlane32_swap_b32_e32 v46, v47
	v_permlane32_swap_b32_e32 v44, v45
	v_permlane32_swap_b32_e32 v38, v39
	v_permlane32_swap_b32_e32 v36, v37
	v_permlane32_swap_b32_e32 v32, v33
	v_cmp_ne_u32_e32 vcc, v35, v96
	s_and_saveexec_b64 s[42:43], vcc
	s_cbranch_execz .LBB0_387
	v_mul_u32_u24_e32 v0, 0x7600, v35
	v_lshlrev_b32_e32 v96, 2, v0
	v_lshl_add_u64 v[0:1], s[44:45], 0, v[96:97]
	v_lshl_add_u64 v[12:13], v[154:155], 2, v[0:1]
	global_load_dwordx4 v[0:3], v[12:13], off offset:16
	global_load_dwordx4 v[4:7], v[12:13], off
	global_load_dwordx4 v[8:11], v[12:13], off offset:528
	s_nop 0
	global_load_dwordx4 v[12:15], v[12:13], off offset:512
	v_mov_b32_e32 v96, v35

.LBB0_465:
	s_add_u32 s58, s42, 0xfffd0080
	s_addc_u32 s59, s43, -1
	s_add_i32 s72, 0, 0x10000
	v_add_u32_e32 v96, s72, v163
	ds_read_b128 v[154:157], v96
	ds_read_b128 v[170:173], v96 offset:1024
	ds_read_b128 v[174:177], v96 offset:2048
	ds_read_b128 v[182:185], v96 offset:3072
	s_cmp_eq_u32 s71, 12
	s_cselect_b32 s61, s53, s59
	s_cselect_b32 s60, s52, s58
	s_cselect_b32 s59, s51, s70
	s_cselect_b32 s58, s68, s69
	v_lshl_add_u64 v[160:161], s[42:43], 0, v[150:151]
	s_add_i32 m0, s27, 0xc000
	ds_read_b128 v[186:189], v168
	ds_read_b128 v[190:193], v168 offset:1024
	ds_read_b128 v[194:197], v168 offset:2048
	ds_read_b128 v[198:201], v168 offset:3072
	ds_read_b128 v[224:227], v168 offset:4096
	ds_read_b128 v[228:231], v168 offset:5120
	global_load_lds_dwordx4 v[160:161], off
	v_lshl_add_u64 v[160:161], s[42:43], 0, v[152:153]
	s_add_i32 m0, s27, 0xe000
	s_mov_b64 exec, s[98:99]
	global_load_lds_dwordx4 v[160:161], off
	s_mov_b64 exec, -1
	s_waitcnt lgkmcnt(8)
	s_setprio 1
	s_barrier
	s_waitcnt lgkmcnt(0)
	v_mfma_f32_16x16x32_bf16 v[134:137], v[154:157], v[186:189], v[134:137]
	v_mfma_f32_16x16x32_bf16 v[130:133], v[174:177], v[186:189], v[130:133]
	v_mfma_f32_16x16x32_bf16 v[92:95], v[154:157], v[194:197], v[92:95]
	v_mfma_f32_16x16x32_bf16 v[88:91], v[174:177], v[194:197], v[88:91]
	v_mfma_f32_16x16x32_bf16 v[76:79], v[154:157], v[224:227], v[76:79]
	v_mfma_f32_16x16x32_bf16 v[72:75], v[174:177], v[224:227], v[72:75]
	v_mfma_f32_16x16x32_bf16 v[134:137], v[170:173], v[190:193], v[134:137]
	v_mfma_f32_16x16x32_bf16 v[130:133], v[182:185], v[190:193], v[130:133]
	v_mfma_f32_16x16x32_bf16 v[92:95], v[170:173], v[198:201], v[92:95]
	v_mfma_f32_16x16x32_bf16 v[88:91], v[182:185], v[198:201], v[88:91]
	v_mfma_f32_16x16x32_bf16 v[76:79], v[170:173], v[228:231], v[76:79]
	v_mfma_f32_16x16x32_bf16 v[72:75], v[182:185], v[228:231], v[72:75]
	s_barrier
	s_setprio 0
	s_add_i32 s80, 0, 0x14000
	s_add_i32 s72, s72, s18
	v_add_u32_e32 v96, s80, v163
	v_lshl_add_u64 v[160:161], s[58:59], 0, v[140:141]
	s_mov_b32 m0, s72
	ds_read_b128 v[232:235], v96
	ds_read_b128 v[236:239], v96 offset:1024
	ds_read_b128 v[240:243], v96 offset:2048
	ds_read_b128 v[244:247], v96 offset:3072
	global_load_lds_dwordx4 v[160:161], off
	v_lshl_add_u64 v[164:165], s[58:59], 0, v[144:145]
	s_add_i32 m0, s72, 0x2000
	s_nop 0
	global_load_lds_dwordx4 v[164:165], off
	s_setprio 1
	s_barrier
	s_waitcnt lgkmcnt(0)
	v_mfma_f32_16x16x32_bf16 v[110:113], v[232:235], v[186:189], v[110:113]
	v_mfma_f32_16x16x32_bf16 v[98:101], v[240:243], v[186:189], v[98:101]
	v_mfma_f32_16x16x32_bf16 v[84:87], v[232:235], v[194:197], v[84:87]
	s_mov_b32 m0, s27
	v_mfma_f32_16x16x32_bf16 v[80:83], v[240:243], v[194:197], v[80:83]
	v_lshl_add_u64 v[202:203], s[60:61], 0, v[138:139]
	v_mfma_f32_16x16x32_bf16 v[68:71], v[232:235], v[224:227], v[68:71]
	v_mfma_f32_16x16x32_bf16 v[64:67], v[240:243], v[224:227], v[64:67]
	v_mfma_f32_16x16x32_bf16 v[110:113], v[236:239], v[190:193], v[110:113]
	v_mfma_f32_16x16x32_bf16 v[98:101], v[244:247], v[190:193], v[98:101]
	v_mfma_f32_16x16x32_bf16 v[84:87], v[236:239], v[198:201], v[84:87]
	v_mfma_f32_16x16x32_bf16 v[80:83], v[244:247], v[198:201], v[80:83]
	v_mfma_f32_16x16x32_bf16 v[68:71], v[236:239], v[228:231], v[68:71]
	v_mfma_f32_16x16x32_bf16 v[64:67], v[244:247], v[228:231], v[64:67]
	s_barrier
	s_setprio 0
	ds_read_b128 v[186:189], v168 offset:16384
	ds_read_b128 v[190:193], v168 offset:17408
	ds_read_b128 v[194:197], v168 offset:18432
	ds_read_b128 v[198:201], v168 offset:19456
	ds_read_b128 v[224:227], v168 offset:20480
	ds_read_b128 v[228:231], v168 offset:21504
	global_load_lds_dwordx4 v[202:203], off
	v_lshl_add_u64 v[248:249], s[60:61], 0, v[142:143]
	s_mov_b32 m0, s28
	s_mov_b64 exec, s[98:99]
	global_load_lds_dwordx4 v[248:249], off
	s_mov_b64 exec, -1
	s_setprio 1
	s_barrier
	s_waitcnt lgkmcnt(0)
	v_mfma_f32_16x16x32_bf16 v[60:63], v[154:157], v[186:189], v[60:63]
	v_mfma_f32_16x16x32_bf16 v[56:59], v[174:177], v[186:189], v[56:59]
	v_mfma_f32_16x16x32_bf16 v[44:47], v[154:157], v[194:197], v[44:47]
	v_mfma_f32_16x16x32_bf16 v[40:43], v[174:177], v[194:197], v[40:43]
	v_mfma_f32_16x16x32_bf16 v[28:31], v[154:157], v[224:227], v[28:31]
	v_mfma_f32_16x16x32_bf16 v[24:27], v[174:177], v[224:227], v[24:27]
	v_mfma_f32_16x16x32_bf16 v[60:63], v[170:173], v[190:193], v[60:63]
	v_mfma_f32_16x16x32_bf16 v[56:59], v[182:185], v[190:193], v[56:59]
	v_mfma_f32_16x16x32_bf16 v[44:47], v[170:173], v[198:201], v[44:47]
	v_mfma_f32_16x16x32_bf16 v[40:43], v[182:185], v[198:201], v[40:43]
	v_mfma_f32_16x16x32_bf16 v[28:31], v[170:173], v[228:231], v[28:31]
	v_mfma_f32_16x16x32_bf16 v[24:27], v[182:185], v[228:231], v[24:27]
	s_barrier
	s_setprio 0
	s_add_u32 s78, s58, 0x40000
	s_addc_u32 s79, s59, 0
	s_add_i32 s72, s80, s18
	v_lshl_add_u64 v[154:155], s[78:79], 0, v[140:141]
	s_mov_b32 m0, s72
	s_nop 0
	global_load_lds_dwordx4 v[154:155], off
	v_lshl_add_u64 v[154:155], s[78:79], 0, v[144:145]
	s_add_i32 m0, s72, 0x2000
	s_nop 0
	global_load_lds_dwordx4 v[154:155], off
	s_waitcnt vmcnt(6)
	s_setprio 1
	s_barrier
	v_mfma_f32_16x16x32_bf16 v[52:55], v[232:235], v[186:189], v[52:55]
	v_mfma_f32_16x16x32_bf16 v[48:51], v[240:243], v[186:189], v[48:51]
	v_mfma_f32_16x16x32_bf16 v[36:39], v[232:235], v[194:197], v[36:39]
	s_add_i32 s72, 0, 0x18000
	v_mfma_f32_16x16x32_bf16 v[32:35], v[240:243], v[194:197], v[32:35]
	v_add_u32_e32 v96, s72, v163
	v_mfma_f32_16x16x32_bf16 v[20:23], v[232:235], v[224:227], v[20:23]
	v_mfma_f32_16x16x32_bf16 v[16:19], v[240:243], v[224:227], v[16:19]
	v_mfma_f32_16x16x32_bf16 v[52:55], v[236:239], v[190:193], v[52:55]
	v_mfma_f32_16x16x32_bf16 v[48:51], v[244:247], v[190:193], v[48:51]
	v_mfma_f32_16x16x32_bf16 v[36:39], v[236:239], v[198:201], v[36:39]
	v_mfma_f32_16x16x32_bf16 v[32:35], v[244:247], v[198:201], v[32:35]
	v_mfma_f32_16x16x32_bf16 v[20:23], v[236:239], v[228:231], v[20:23]
	v_mfma_f32_16x16x32_bf16 v[16:19], v[244:247], v[228:231], v[16:19]
	s_barrier
	s_setprio 0
	ds_read_b128 v[154:157], v96
	ds_read_b128 v[170:173], v96 offset:1024
	ds_read_b128 v[174:177], v96 offset:2048
	ds_read_b128 v[182:185], v96 offset:3072
	s_add_u32 s60, s60, 0x30000
	s_addc_u32 s61, s61, 0
	s_mov_b32 m0, s37
	v_lshl_add_u64 v[232:233], s[60:61], 0, v[138:139]
	ds_read_b128 v[186:189], v168 offset:32768
	ds_read_b128 v[190:193], v168 offset:33792
	ds_read_b128 v[194:197], v168 offset:34816
	ds_read_b128 v[198:201], v168 offset:35840
	ds_read_b128 v[224:227], v168 offset:36864
	ds_read_b128 v[228:231], v168 offset:37888
	global_load_lds_dwordx4 v[232:233], off
	v_lshl_add_u64 v[232:233], s[60:61], 0, v[142:143]
	s_mov_b32 m0, s57
	s_mov_b64 exec, s[98:99]
	global_load_lds_dwordx4 v[232:233], off
	s_mov_b64 exec, -1
	s_waitcnt lgkmcnt(8)
	s_setprio 1
	s_barrier
	s_waitcnt lgkmcnt(0)
	v_mfma_f32_16x16x32_bf16 v[134:137], v[154:157], v[186:189], v[134:137]
	v_mfma_f32_16x16x32_bf16 v[130:133], v[174:177], v[186:189], v[130:133]
	v_mfma_f32_16x16x32_bf16 v[92:95], v[154:157], v[194:197], v[92:95]
	v_mfma_f32_16x16x32_bf16 v[88:91], v[174:177], v[194:197], v[88:91]
	v_mfma_f32_16x16x32_bf16 v[76:79], v[154:157], v[224:227], v[76:79]
	v_mfma_f32_16x16x32_bf16 v[72:75], v[174:177], v[224:227], v[72:75]
	v_mfma_f32_16x16x32_bf16 v[134:137], v[170:173], v[190:193], v[134:137]
	v_mfma_f32_16x16x32_bf16 v[130:133], v[182:185], v[190:193], v[130:133]
	v_mfma_f32_16x16x32_bf16 v[92:95], v[170:173], v[198:201], v[92:95]
	v_mfma_f32_16x16x32_bf16 v[88:91], v[182:185], v[198:201], v[88:91]
	v_mfma_f32_16x16x32_bf16 v[76:79], v[170:173], v[228:231], v[76:79]
	v_mfma_f32_16x16x32_bf16 v[72:75], v[182:185], v[228:231], v[72:75]
	s_barrier
	s_setprio 0
	s_add_i32 s60, 0, 0x1c000
	s_add_i32 s61, s72, s18
	v_add_u32_e32 v96, s60, v163
	v_lshl_add_u64 v[160:161], v[160:161], 0, s[6:7]
	s_mov_b32 m0, s61
	ds_read_b128 v[232:235], v96
	ds_read_b128 v[236:239], v96 offset:1024
	ds_read_b128 v[240:243], v96 offset:2048
	ds_read_b128 v[244:247], v96 offset:3072
	global_load_lds_dwordx4 v[160:161], off
	v_lshl_add_u64 v[160:161], v[164:165], 0, s[6:7]
	s_add_i32 m0, s61, 0x2000
	s_nop 0
	global_load_lds_dwordx4 v[160:161], off
	s_setprio 1
	s_barrier
	s_waitcnt lgkmcnt(0)
	v_mfma_f32_16x16x32_bf16 v[110:113], v[232:235], v[186:189], v[110:113]
	v_mfma_f32_16x16x32_bf16 v[98:101], v[240:243], v[186:189], v[98:101]
	v_mfma_f32_16x16x32_bf16 v[84:87], v[232:235], v[194:197], v[84:87]
	s_mov_b32 m0, s62
	v_mfma_f32_16x16x32_bf16 v[80:83], v[240:243], v[194:197], v[80:83]
	v_lshl_add_u64 v[160:161], v[202:203], 0, s[6:7]
	v_mfma_f32_16x16x32_bf16 v[68:71], v[232:235], v[224:227], v[68:71]
	v_mfma_f32_16x16x32_bf16 v[64:67], v[240:243], v[224:227], v[64:67]
	v_mfma_f32_16x16x32_bf16 v[110:113], v[236:239], v[190:193], v[110:113]
	v_mfma_f32_16x16x32_bf16 v[98:101], v[244:247], v[190:193], v[98:101]
	v_mfma_f32_16x16x32_bf16 v[84:87], v[236:239], v[198:201], v[84:87]
	v_mfma_f32_16x16x32_bf16 v[80:83], v[244:247], v[198:201], v[80:83]
	v_mfma_f32_16x16x32_bf16 v[68:71], v[236:239], v[228:231], v[68:71]
	v_mfma_f32_16x16x32_bf16 v[64:67], v[244:247], v[228:231], v[64:67]
	s_barrier
	s_setprio 0
	ds_read_b128 v[186:189], v168 offset:49152
	ds_read_b128 v[190:193], v168 offset:50176
	ds_read_b128 v[194:197], v168 offset:51200
	ds_read_b128 v[198:201], v168 offset:52224
	ds_read_b128 v[224:227], v168 offset:53248
	ds_read_b128 v[228:231], v168 offset:54272
	global_load_lds_dwordx4 v[160:161], off
	v_lshl_add_u64 v[160:161], v[248:249], 0, s[6:7]
	s_mov_b32 m0, s63
	s_mov_b64 exec, s[98:99]
	global_load_lds_dwordx4 v[160:161], off
	s_mov_b64 exec, -1
	s_setprio 1
	s_barrier
	s_waitcnt lgkmcnt(0)
	v_mfma_f32_16x16x32_bf16 v[60:63], v[154:157], v[186:189], v[60:63]
	v_mfma_f32_16x16x32_bf16 v[56:59], v[174:177], v[186:189], v[56:59]
	v_mfma_f32_16x16x32_bf16 v[44:47], v[154:157], v[194:197], v[44:47]
	v_mfma_f32_16x16x32_bf16 v[40:43], v[174:177], v[194:197], v[40:43]
	v_mfma_f32_16x16x32_bf16 v[28:31], v[154:157], v[224:227], v[28:31]
	v_mfma_f32_16x16x32_bf16 v[24:27], v[174:177], v[224:227], v[24:27]
	v_mfma_f32_16x16x32_bf16 v[60:63], v[170:173], v[190:193], v[60:63]
	v_mfma_f32_16x16x32_bf16 v[56:59], v[182:185], v[190:193], v[56:59]
	v_mfma_f32_16x16x32_bf16 v[44:47], v[170:173], v[198:201], v[44:47]
	v_mfma_f32_16x16x32_bf16 v[40:43], v[182:185], v[198:201], v[40:43]
	v_mfma_f32_16x16x32_bf16 v[28:31], v[170:173], v[228:231], v[28:31]
	v_mfma_f32_16x16x32_bf16 v[24:27], v[182:185], v[228:231], v[24:27]
	s_barrier
	s_setprio 0
	s_add_u32 s58, s58, 0x40080
	s_addc_u32 s59, s59, 0
	s_add_i32 s60, s60, s18
	v_lshl_add_u64 v[154:155], s[58:59], 0, v[140:141]
	s_mov_b32 m0, s60
	s_nop 0
	global_load_lds_dwordx4 v[154:155], off
	v_lshl_add_u64 v[154:155], s[58:59], 0, v[144:145]
	s_add_i32 m0, s60, 0x2000
	s_nop 0
	global_load_lds_dwordx4 v[154:155], off
	s_waitcnt vmcnt(6)
	s_setprio 1
	s_barrier
	v_mfma_f32_16x16x32_bf16 v[52:55], v[232:235], v[186:189], v[52:55]
	v_mfma_f32_16x16x32_bf16 v[48:51], v[240:243], v[186:189], v[48:51]
	v_mfma_f32_16x16x32_bf16 v[36:39], v[232:235], v[194:197], v[36:39]
	s_add_i32 s71, s71, 2
	v_mfma_f32_16x16x32_bf16 v[32:35], v[240:243], v[194:197], v[32:35]
	s_add_u32 s42, s42, 0x100
	v_mfma_f32_16x16x32_bf16 v[20:23], v[232:235], v[224:227], v[20:23]
	s_addc_u32 s43, s43, 0
	v_mfma_f32_16x16x32_bf16 v[16:19], v[240:243], v[224:227], v[16:19]
	s_add_u32 s69, s69, 0x100
	v_mfma_f32_16x16x32_bf16 v[52:55], v[236:239], v[190:193], v[52:55]
	s_addc_u32 s70, s70, 0
	v_mfma_f32_16x16x32_bf16 v[48:51], v[244:247], v[190:193], v[48:51]
	s_cmp_gt_u32 s71, 13
	v_mfma_f32_16x16x32_bf16 v[36:39], v[236:239], v[198:201], v[36:39]
	v_mfma_f32_16x16x32_bf16 v[32:35], v[244:247], v[198:201], v[32:35]
	v_mfma_f32_16x16x32_bf16 v[20:23], v[236:239], v[228:231], v[20:23]
	v_mfma_f32_16x16x32_bf16 v[16:19], v[244:247], v[228:231], v[16:19]
	s_barrier
	s_setprio 0
	s_cbranch_scc0 .LBB0_465
	s_mul_i32 s42, s67, 0xc0
	s_add_i32 s42, s42, s19
	s_cmpk_lt_u32 s42, 0x2000
	s_cselect_b32 s43, 1, 2
	v_or_b32_e32 v156, s42, v159
	v_mov_b32_e32 v96, s43
	v_cmp_lt_i32_e32 vcc, s23, v156
	v_add_u32_e32 v160, 16, v156
	v_lshl_or_b32 v154, s56, 8, v166
	v_cndmask_b32_e32 v169, 0, v96, vcc
	s_waitcnt vmcnt(0)
	v_add_f32_e32 v96, v126, v127
	v_add_f32_e32 v126, v128, v129
	v_add_f32_e32 v96, v96, v126
	v_mov_b32_e32 v126, v96
	s_nop 1
	v_permlane16_swap_b32_e32 v96, v126
	v_add_f32_e32 v96, v96, v126
	v_mov_b32_e32 v126, v96
	s_nop 1
	v_permlane32_swap_b32_e32 v96, v126
	v_add_f32_e32 v96, v96, v126
	v_fmamk_f32 v96, v96, 0x3a800000, v207
	v_rsq_f32_e32 v162, v96
	v_add_f32_e32 v96, v122, v123
	v_add_f32_e32 v122, v124, v125
	v_add_f32_e32 v96, v96, v122
	v_mov_b32_e32 v122, v96
	s_nop 1
	v_permlane16_swap_b32_e32 v96, v122
	v_add_f32_e32 v96, v96, v122
	v_mov_b32_e32 v122, v96
	s_nop 1
	v_permlane32_swap_b32_e32 v96, v122
	v_add_f32_e32 v96, v96, v122
	v_fmamk_f32 v96, v96, 0x3a800000, v207
	v_rsq_f32_e32 v158, v96
	v_add_f32_e32 v96, v118, v119
	v_add_f32_e32 v118, v120, v121
	v_add_f32_e32 v96, v96, v118
	v_mov_b32_e32 v118, v96
	s_nop 1
	v_permlane16_swap_b32_e32 v96, v118
	v_add_f32_e32 v96, v96, v118
	v_mov_b32_e32 v118, v96
	s_nop 1
	v_permlane32_swap_b32_e32 v96, v118
	v_add_f32_e32 v96, v96, v118
	v_fmamk_f32 v96, v96, 0x3a800000, v207
	v_rsq_f32_e32 v128, v96
	v_add_f32_e32 v96, v114, v115
	v_add_f32_e32 v114, v116, v117
	v_add_f32_e32 v96, v96, v114
	v_mov_b32_e32 v114, v96
	s_nop 1
	v_permlane16_swap_b32_e32 v96, v114
	v_add_f32_e32 v96, v96, v114
	v_mov_b32_e32 v114, v96
	s_nop 1
	v_permlane32_swap_b32_e32 v96, v114
	v_add_f32_e32 v96, v96, v114
	v_fmamk_f32 v96, v96, 0x3a800000, v207
	v_rsq_f32_e32 v126, v96
	v_add_f32_e32 v96, v106, v107
	v_add_f32_e32 v106, v108, v109
	v_add_f32_e32 v96, v96, v106
	v_mov_b32_e32 v106, v96
	s_nop 1
	v_permlane16_swap_b32_e32 v96, v106
	v_add_f32_e32 v96, v96, v106
	v_mov_b32_e32 v106, v96
	s_nop 1
	v_permlane32_swap_b32_e32 v96, v106
	v_add_f32_e32 v96, v96, v106
	v_fmamk_f32 v96, v96, 0x3a800000, v207
	v_rsq_f32_e32 v124, v96
	v_add_f32_e32 v96, v102, v103
	v_add_f32_e32 v102, v104, v105
	v_add_f32_e32 v96, v96, v102
	v_mov_b32_e32 v102, v96
	s_nop 1
	v_permlane16_swap_b32_e32 v96, v102
	v_add_f32_e32 v96, v96, v102
	v_mov_b32_e32 v102, v96
	s_nop 1
	v_permlane32_swap_b32_e32 v96, v102
	v_add_f32_e32 v96, v96, v102
	v_fmamk_f32 v96, v96, 0x3a800000, v207
	v_rsq_f32_e32 v122, v96
	s_mov_b64 s[58:59], -1
	s_cmp_gt_i32 s56, 3
	v_ashrrev_i32_e32 v157, 31, v156
	v_cmp_lt_i32_e32 vcc, s26, v156
	v_cmp_gt_u32_e64 s[42:43], s24, v160
	s_cbranch_scc0 .LBB0_478
	v_lshlrev_b64 v[102:103], 11, v[156:157]
	v_lshl_add_u32 v96, s56, 7, v167
	v_lshl_add_u64 v[102:103], s[48:49], 0, v[102:103]
	v_lshl_add_u64 v[106:107], v[96:97], 1, v[102:103]
	v_pk_fma_f32 v[102:103], v[136:137], v[162:163], v[6:7] op_sel_hi:[1,0,1]
	v_pk_fma_f32 v[104:105], v[134:135], v[162:163], v[4:5] op_sel_hi:[1,0,1]
	v_pk_fma_f32 v[108:109], v[112:113], v[162:163], v[14:15] op_sel_hi:[1,0,1]
	v_pk_fma_f32 v[114:115], v[110:111], v[162:163], v[12:13] op_sel_hi:[1,0,1]
	v_pk_mul_f32 v[108:109], v[102:103], v[108:109]
	v_pk_mul_f32 v[102:103], v[104:105], v[114:115]
	v_pk_fma_f32 v[104:105], v[132:133], v[162:163], v[2:3] op_sel_hi:[1,0,1]
	v_pk_fma_f32 v[114:115], v[130:131], v[162:163], v[0:1] op_sel_hi:[1,0,1]
	v_pk_fma_f32 v[116:117], v[100:101], v[162:163], v[10:11] op_sel_hi:[1,0,1]
	v_pk_fma_f32 v[118:119], v[98:99], v[162:163], v[8:9] op_sel_hi:[1,0,1]
	v_pk_mul_f32 v[116:117], v[104:105], v[116:117]
	v_pk_mul_f32 v[104:105], v[114:115], v[118:119]
	v_cvt_pk_bf16_f32 v102, v102, v103
	v_cvt_pk_bf16_f32 v103, v108, v109
	v_mov_b64_e32 v[120:121], v[14:15]
	v_cvt_pk_bf16_f32 v104, v104, v105
	v_cvt_pk_bf16_f32 v105, v116, v117
	global_store_dwordx4 v[106:107], v[102:105], off
	v_mov_b64_e32 v[116:117], v[10:11]
	v_mov_b64_e32 v[108:109], v[6:7]
	v_cndmask_b32_e64 v102, 2, 1, s[42:43]
	v_cndmask_b32_e32 v125, 0, v102, vcc
	v_mov_b64_e32 v[104:105], v[2:3]
	v_mov_b32_e32 v155, v97
	v_cmp_ne_u32_e32 vcc, v125, v169
	v_mov_b64_e32 v[114:115], v[8:9]
	v_mov_b64_e32 v[102:103], v[0:1]
	v_mov_b64_e32 v[118:119], v[12:13]
	v_mov_b64_e32 v[106:107], v[4:5]
	v_mov_b32_e32 v123, v169
	s_and_saveexec_b64 s[42:43], vcc
	s_cbranch_execz .LBB0_469
	v_mul_u32_u24_e32 v102, 0x7600, v125
	v_lshlrev_b32_e32 v102, 2, v102
	v_mov_b32_e32 v103, v97
	v_lshl_add_u64 v[102:103], s[44:45], 0, v[102:103]
	v_lshl_add_u64 v[118:119], v[154:155], 2, v[102:103]
	global_load_dwordx4 v[102:105], v[118:119], off offset:16
	global_load_dwordx4 v[106:109], v[118:119], off
	global_load_dwordx4 v[114:117], v[118:119], off offset:528
	s_nop 0
	global_load_dwordx4 v[118:121], v[118:119], off offset:512
	v_mov_b32_e32 v123, v125

.LBB0_557:
	s_add_u32 s60, s58, 0xfffc0080
	s_addc_u32 s61, s59, -1
	s_add_i32 s72, 0, 0x10000
	v_add_u32_e32 v96, s72, v193
	ds_read_b128 v[80:83], v96
	ds_read_b128 v[88:91], v96 offset:1024
	ds_read_b128 v[102:105], v96 offset:2048
	ds_read_b128 v[106:109], v96 offset:3072
	s_cmp_eq_u32 s71, 12
	s_cselect_b32 s63, s49, s61
	s_cselect_b32 s62, s67, s60
	s_cselect_b32 s61, s47, s70
	s_cselect_b32 s60, s68, s69
	v_lshl_add_u64 v[176:177], s[58:59], 0, v[156:157]
	s_add_i32 m0, s27, 0xc000
	ds_read_b128 v[160:163], v195
	ds_read_b128 v[164:167], v195 offset:1024
	ds_read_b128 v[168:171], v195 offset:2048
	ds_read_b128 v[172:175], v195 offset:3072
	ds_read_b128 v[182:185], v195 offset:4096
	ds_read_b128 v[186:189], v195 offset:5120
	ds_read_b128 v[196:199], v195 offset:6144
	ds_read_b128 v[200:203], v195 offset:7168
	global_load_lds_dwordx4 v[176:177], off
	v_lshl_add_u64 v[176:177], s[58:59], 0, v[158:159]
	s_add_i32 m0, s27, 0xe000
	s_nop 0
	global_load_lds_dwordx4 v[176:177], off
	s_waitcnt lgkmcnt(8)
	s_setprio 1
	s_barrier
	s_waitcnt lgkmcnt(0)
	v_mfma_f32_16x16x32_bf16 v[142:145], v[80:83], v[160:163], v[142:145]
	v_mfma_f32_16x16x32_bf16 v[138:141], v[102:105], v[160:163], v[138:141]
	v_mfma_f32_16x16x32_bf16 v[126:129], v[80:83], v[168:171], v[126:129]
	v_mfma_f32_16x16x32_bf16 v[122:125], v[102:105], v[168:171], v[122:125]
	v_mfma_f32_16x16x32_bf16 v[110:113], v[80:83], v[182:185], v[110:113]
	v_mfma_f32_16x16x32_bf16 v[98:101], v[102:105], v[182:185], v[98:101]
	v_mfma_f32_16x16x32_bf16 v[76:79], v[80:83], v[196:199], v[76:79]
	v_mfma_f32_16x16x32_bf16 v[72:75], v[102:105], v[196:199], v[72:75]
	v_mfma_f32_16x16x32_bf16 v[142:145], v[88:91], v[164:167], v[142:145]
	v_mfma_f32_16x16x32_bf16 v[138:141], v[106:109], v[164:167], v[138:141]
	v_mfma_f32_16x16x32_bf16 v[126:129], v[88:91], v[172:175], v[126:129]
	v_mfma_f32_16x16x32_bf16 v[122:125], v[106:109], v[172:175], v[122:125]
	v_mfma_f32_16x16x32_bf16 v[110:113], v[88:91], v[186:189], v[110:113]
	v_mfma_f32_16x16x32_bf16 v[98:101], v[106:109], v[186:189], v[98:101]
	v_mfma_f32_16x16x32_bf16 v[76:79], v[88:91], v[200:203], v[76:79]
	v_mfma_f32_16x16x32_bf16 v[72:75], v[106:109], v[200:203], v[72:75]
	s_barrier
	s_setprio 0
	s_add_i32 s76, 0, 0x14000
	s_add_i32 s72, s72, s18
	v_add_u32_e32 v96, s76, v193
	v_lshl_add_u64 v[176:177], s[60:61], 0, v[150:151]
	s_mov_b32 m0, s72
	ds_read_b128 v[224:227], v96
	ds_read_b128 v[228:231], v96 offset:1024
	ds_read_b128 v[232:235], v96 offset:2048
	ds_read_b128 v[236:239], v96 offset:3072
	global_load_lds_dwordx4 v[176:177], off
	v_lshl_add_u64 v[190:191], s[60:61], 0, v[146:147]
	s_add_i32 m0, s72, 0x2000
	s_nop 0
	global_load_lds_dwordx4 v[190:191], off
	s_setprio 1
	s_barrier
	s_waitcnt lgkmcnt(0)
	v_mfma_f32_16x16x32_bf16 v[134:137], v[224:227], v[160:163], v[134:137]
	v_mfma_f32_16x16x32_bf16 v[130:133], v[232:235], v[160:163], v[130:133]
	v_mfma_f32_16x16x32_bf16 v[118:121], v[224:227], v[168:171], v[118:121]
	s_mov_b32 m0, s27
	v_mfma_f32_16x16x32_bf16 v[114:117], v[232:235], v[168:171], v[114:117]
	v_lshl_add_u64 v[240:241], s[62:63], 0, v[152:153]
	v_mfma_f32_16x16x32_bf16 v[92:95], v[224:227], v[182:185], v[92:95]
	v_mfma_f32_16x16x32_bf16 v[84:87], v[232:235], v[182:185], v[84:87]
	v_mfma_f32_16x16x32_bf16 v[68:71], v[224:227], v[196:199], v[68:71]
	v_mfma_f32_16x16x32_bf16 v[64:67], v[232:235], v[196:199], v[64:67]
	v_mfma_f32_16x16x32_bf16 v[134:137], v[228:231], v[164:167], v[134:137]
	v_mfma_f32_16x16x32_bf16 v[130:133], v[236:239], v[164:167], v[130:133]
	v_mfma_f32_16x16x32_bf16 v[118:121], v[228:231], v[172:175], v[118:121]
	v_mfma_f32_16x16x32_bf16 v[114:117], v[236:239], v[172:175], v[114:117]
	v_mfma_f32_16x16x32_bf16 v[92:95], v[228:231], v[186:189], v[92:95]
	v_mfma_f32_16x16x32_bf16 v[84:87], v[236:239], v[186:189], v[84:87]
	v_mfma_f32_16x16x32_bf16 v[68:71], v[228:231], v[200:203], v[68:71]
	v_mfma_f32_16x16x32_bf16 v[64:67], v[236:239], v[200:203], v[64:67]
	s_barrier
	s_setprio 0
	ds_read_b128 v[160:163], v195 offset:16384
	ds_read_b128 v[164:167], v195 offset:17408
	ds_read_b128 v[168:171], v195 offset:18432
	ds_read_b128 v[172:175], v195 offset:19456
	ds_read_b128 v[182:185], v195 offset:20480
	ds_read_b128 v[186:189], v195 offset:21504
	ds_read_b128 v[196:199], v195 offset:22528
	ds_read_b128 v[200:203], v195 offset:23552
	global_load_lds_dwordx4 v[240:241], off
	v_lshl_add_u64 v[242:243], s[62:63], 0, v[148:149]
	s_mov_b32 m0, s28
	s_nop 0
	global_load_lds_dwordx4 v[242:243], off
	s_setprio 1
	s_barrier
	s_waitcnt lgkmcnt(0)
	v_mfma_f32_16x16x32_bf16 v[60:63], v[80:83], v[160:163], v[60:63]
	v_mfma_f32_16x16x32_bf16 v[56:59], v[102:105], v[160:163], v[56:59]
	v_mfma_f32_16x16x32_bf16 v[44:47], v[80:83], v[168:171], v[44:47]
	v_mfma_f32_16x16x32_bf16 v[40:43], v[102:105], v[168:171], v[40:43]
	v_mfma_f32_16x16x32_bf16 v[28:31], v[80:83], v[182:185], v[28:31]
	v_mfma_f32_16x16x32_bf16 v[24:27], v[102:105], v[182:185], v[24:27]
	v_mfma_f32_16x16x32_bf16 v[12:15], v[80:83], v[196:199], v[12:15]
	v_mfma_f32_16x16x32_bf16 v[8:11], v[102:105], v[196:199], v[8:11]
	v_mfma_f32_16x16x32_bf16 v[60:63], v[88:91], v[164:167], v[60:63]
	v_mfma_f32_16x16x32_bf16 v[56:59], v[106:109], v[164:167], v[56:59]
	v_mfma_f32_16x16x32_bf16 v[44:47], v[88:91], v[172:175], v[44:47]
	v_mfma_f32_16x16x32_bf16 v[40:43], v[106:109], v[172:175], v[40:43]
	v_mfma_f32_16x16x32_bf16 v[28:31], v[88:91], v[186:189], v[28:31]
	v_mfma_f32_16x16x32_bf16 v[24:27], v[106:109], v[186:189], v[24:27]
	v_mfma_f32_16x16x32_bf16 v[12:15], v[88:91], v[200:203], v[12:15]
	v_mfma_f32_16x16x32_bf16 v[8:11], v[106:109], v[200:203], v[8:11]
	s_barrier
	s_setprio 0
	s_add_u32 s74, s60, 0x40000
	s_addc_u32 s75, s61, 0
	s_add_i32 s72, s76, s18
	v_lshl_add_u64 v[80:81], s[74:75], 0, v[150:151]
	s_mov_b32 m0, s72
	s_nop 0
	global_load_lds_dwordx4 v[80:81], off
	v_lshl_add_u64 v[80:81], s[74:75], 0, v[146:147]
	s_add_i32 m0, s72, 0x2000
	s_nop 0
	global_load_lds_dwordx4 v[80:81], off
	s_waitcnt vmcnt(6)
	s_setprio 1
	s_barrier
	v_mfma_f32_16x16x32_bf16 v[52:55], v[224:227], v[160:163], v[52:55]
	v_mfma_f32_16x16x32_bf16 v[48:51], v[232:235], v[160:163], v[48:51]
	v_mfma_f32_16x16x32_bf16 v[36:39], v[224:227], v[168:171], v[36:39]
	s_add_i32 s72, 0, 0x18000
	v_mfma_f32_16x16x32_bf16 v[32:35], v[232:235], v[168:171], v[32:35]
	v_add_u32_e32 v96, s72, v193
	v_mfma_f32_16x16x32_bf16 v[20:23], v[224:227], v[182:185], v[20:23]
	v_mfma_f32_16x16x32_bf16 v[16:19], v[232:235], v[182:185], v[16:19]
	v_mfma_f32_16x16x32_bf16 v[4:7], v[224:227], v[196:199], v[4:7]
	v_mfma_f32_16x16x32_bf16 v[0:3], v[232:235], v[196:199], v[0:3]
	v_mfma_f32_16x16x32_bf16 v[52:55], v[228:231], v[164:167], v[52:55]
	v_mfma_f32_16x16x32_bf16 v[48:51], v[236:239], v[164:167], v[48:51]
	v_mfma_f32_16x16x32_bf16 v[36:39], v[228:231], v[172:175], v[36:39]
	v_mfma_f32_16x16x32_bf16 v[32:35], v[236:239], v[172:175], v[32:35]
	v_mfma_f32_16x16x32_bf16 v[20:23], v[228:231], v[186:189], v[20:23]
	v_mfma_f32_16x16x32_bf16 v[16:19], v[236:239], v[186:189], v[16:19]
	v_mfma_f32_16x16x32_bf16 v[4:7], v[228:231], v[200:203], v[4:7]
	v_mfma_f32_16x16x32_bf16 v[0:3], v[236:239], v[200:203], v[0:3]
	s_barrier
	s_setprio 0
	ds_read_b128 v[80:83], v96
	ds_read_b128 v[88:91], v96 offset:1024
	ds_read_b128 v[102:105], v96 offset:2048
	ds_read_b128 v[106:109], v96 offset:3072
	s_add_u32 s62, s62, 0x40000
	s_addc_u32 s63, s63, 0
	s_mov_b32 m0, s37
	v_lshl_add_u64 v[224:225], s[62:63], 0, v[152:153]
	ds_read_b128 v[160:163], v195 offset:32768
	ds_read_b128 v[164:167], v195 offset:33792
	ds_read_b128 v[168:171], v195 offset:34816
	ds_read_b128 v[172:175], v195 offset:35840
	ds_read_b128 v[182:185], v195 offset:36864
	ds_read_b128 v[186:189], v195 offset:37888
	ds_read_b128 v[196:199], v195 offset:38912
	ds_read_b128 v[200:203], v195 offset:39936
	global_load_lds_dwordx4 v[224:225], off
	v_lshl_add_u64 v[224:225], s[62:63], 0, v[148:149]
	s_mov_b32 m0, s56
	s_nop 0
	global_load_lds_dwordx4 v[224:225], off
	s_waitcnt lgkmcnt(8)
	s_setprio 1
	s_barrier
	s_waitcnt lgkmcnt(0)
	v_mfma_f32_16x16x32_bf16 v[142:145], v[80:83], v[160:163], v[142:145]
	v_mfma_f32_16x16x32_bf16 v[138:141], v[102:105], v[160:163], v[138:141]
	v_mfma_f32_16x16x32_bf16 v[126:129], v[80:83], v[168:171], v[126:129]
	v_mfma_f32_16x16x32_bf16 v[122:125], v[102:105], v[168:171], v[122:125]
	v_mfma_f32_16x16x32_bf16 v[110:113], v[80:83], v[182:185], v[110:113]
	v_mfma_f32_16x16x32_bf16 v[98:101], v[102:105], v[182:185], v[98:101]
	v_mfma_f32_16x16x32_bf16 v[76:79], v[80:83], v[196:199], v[76:79]
	v_mfma_f32_16x16x32_bf16 v[72:75], v[102:105], v[196:199], v[72:75]
	v_mfma_f32_16x16x32_bf16 v[142:145], v[88:91], v[164:167], v[142:145]
	v_mfma_f32_16x16x32_bf16 v[138:141], v[106:109], v[164:167], v[138:141]
	v_mfma_f32_16x16x32_bf16 v[126:129], v[88:91], v[172:175], v[126:129]
	v_mfma_f32_16x16x32_bf16 v[122:125], v[106:109], v[172:175], v[122:125]
	v_mfma_f32_16x16x32_bf16 v[110:113], v[88:91], v[186:189], v[110:113]
	v_mfma_f32_16x16x32_bf16 v[98:101], v[106:109], v[186:189], v[98:101]
	v_mfma_f32_16x16x32_bf16 v[76:79], v[88:91], v[200:203], v[76:79]
	v_mfma_f32_16x16x32_bf16 v[72:75], v[106:109], v[200:203], v[72:75]
	s_barrier
	s_setprio 0
	s_add_i32 s62, 0, 0x1c000
	s_add_i32 s63, s72, s18
	v_add_u32_e32 v96, s62, v193
	v_lshl_add_u64 v[176:177], v[176:177], 0, s[6:7]
	s_mov_b32 m0, s63
	ds_read_b128 v[224:227], v96
	ds_read_b128 v[228:231], v96 offset:1024
	ds_read_b128 v[232:235], v96 offset:2048
	ds_read_b128 v[236:239], v96 offset:3072
	global_load_lds_dwordx4 v[176:177], off
	v_lshl_add_u64 v[176:177], v[190:191], 0, s[6:7]
	s_add_i32 m0, s63, 0x2000
	s_nop 0
	global_load_lds_dwordx4 v[176:177], off
	s_setprio 1
	s_barrier
	s_waitcnt lgkmcnt(0)
	v_mfma_f32_16x16x32_bf16 v[134:137], v[224:227], v[160:163], v[134:137]
	v_mfma_f32_16x16x32_bf16 v[130:133], v[232:235], v[160:163], v[130:133]
	v_mfma_f32_16x16x32_bf16 v[118:121], v[224:227], v[168:171], v[118:121]
	s_mov_b32 m0, s64
	v_mfma_f32_16x16x32_bf16 v[114:117], v[232:235], v[168:171], v[114:117]
	v_lshl_add_u64 v[176:177], v[240:241], 0, s[6:7]
	v_mfma_f32_16x16x32_bf16 v[92:95], v[224:227], v[182:185], v[92:95]
	v_mfma_f32_16x16x32_bf16 v[84:87], v[232:235], v[182:185], v[84:87]
	v_mfma_f32_16x16x32_bf16 v[68:71], v[224:227], v[196:199], v[68:71]
	v_mfma_f32_16x16x32_bf16 v[64:67], v[232:235], v[196:199], v[64:67]
	v_mfma_f32_16x16x32_bf16 v[134:137], v[228:231], v[164:167], v[134:137]
	v_mfma_f32_16x16x32_bf16 v[130:133], v[236:239], v[164:167], v[130:133]
	v_mfma_f32_16x16x32_bf16 v[118:121], v[228:231], v[172:175], v[118:121]
	v_mfma_f32_16x16x32_bf16 v[114:117], v[236:239], v[172:175], v[114:117]
	v_mfma_f32_16x16x32_bf16 v[92:95], v[228:231], v[186:189], v[92:95]
	v_mfma_f32_16x16x32_bf16 v[84:87], v[236:239], v[186:189], v[84:87]
	v_mfma_f32_16x16x32_bf16 v[68:71], v[228:231], v[200:203], v[68:71]
	v_mfma_f32_16x16x32_bf16 v[64:67], v[236:239], v[200:203], v[64:67]
	s_barrier
	s_setprio 0
	ds_read_b128 v[160:163], v195 offset:49152
	ds_read_b128 v[164:167], v195 offset:50176
	ds_read_b128 v[168:171], v195 offset:51200
	ds_read_b128 v[172:175], v195 offset:52224
	ds_read_b128 v[182:185], v195 offset:53248
	ds_read_b128 v[186:189], v195 offset:54272
	ds_read_b128 v[196:199], v195 offset:55296
	ds_read_b128 v[200:203], v195 offset:56320
	global_load_lds_dwordx4 v[176:177], off
	v_lshl_add_u64 v[176:177], v[242:243], 0, s[6:7]
	s_mov_b32 m0, s65
	s_nop 0
	global_load_lds_dwordx4 v[176:177], off
	s_setprio 1
	s_barrier
	s_waitcnt lgkmcnt(0)
	v_mfma_f32_16x16x32_bf16 v[60:63], v[80:83], v[160:163], v[60:63]
	v_mfma_f32_16x16x32_bf16 v[56:59], v[102:105], v[160:163], v[56:59]
	v_mfma_f32_16x16x32_bf16 v[44:47], v[80:83], v[168:171], v[44:47]
	v_mfma_f32_16x16x32_bf16 v[40:43], v[102:105], v[168:171], v[40:43]
	v_mfma_f32_16x16x32_bf16 v[28:31], v[80:83], v[182:185], v[28:31]
	v_mfma_f32_16x16x32_bf16 v[24:27], v[102:105], v[182:185], v[24:27]
	v_mfma_f32_16x16x32_bf16 v[12:15], v[80:83], v[196:199], v[12:15]
	v_mfma_f32_16x16x32_bf16 v[8:11], v[102:105], v[196:199], v[8:11]
	v_mfma_f32_16x16x32_bf16 v[60:63], v[88:91], v[164:167], v[60:63]
	v_mfma_f32_16x16x32_bf16 v[56:59], v[106:109], v[164:167], v[56:59]
	v_mfma_f32_16x16x32_bf16 v[44:47], v[88:91], v[172:175], v[44:47]
	v_mfma_f32_16x16x32_bf16 v[40:43], v[106:109], v[172:175], v[40:43]
	v_mfma_f32_16x16x32_bf16 v[28:31], v[88:91], v[186:189], v[28:31]
	v_mfma_f32_16x16x32_bf16 v[24:27], v[106:109], v[186:189], v[24:27]
	v_mfma_f32_16x16x32_bf16 v[12:15], v[88:91], v[200:203], v[12:15]
	v_mfma_f32_16x16x32_bf16 v[8:11], v[106:109], v[200:203], v[8:11]
	s_barrier
	s_setprio 0
	s_add_u32 s60, s60, 0x40080
	s_addc_u32 s61, s61, 0
	s_add_i32 s62, s62, s18
	v_lshl_add_u64 v[80:81], s[60:61], 0, v[150:151]
	s_mov_b32 m0, s62
	s_nop 0
	global_load_lds_dwordx4 v[80:81], off
	v_lshl_add_u64 v[80:81], s[60:61], 0, v[146:147]
	s_add_i32 m0, s62, 0x2000
	s_nop 0
	global_load_lds_dwordx4 v[80:81], off
	s_waitcnt vmcnt(6)
	s_setprio 1
	s_barrier
	v_mfma_f32_16x16x32_bf16 v[52:55], v[224:227], v[160:163], v[52:55]
	v_mfma_f32_16x16x32_bf16 v[48:51], v[232:235], v[160:163], v[48:51]
	v_mfma_f32_16x16x32_bf16 v[36:39], v[224:227], v[168:171], v[36:39]
	s_add_i32 s71, s71, 2
	v_mfma_f32_16x16x32_bf16 v[32:35], v[232:235], v[168:171], v[32:35]
	s_add_u32 s58, s58, 0x100
	v_mfma_f32_16x16x32_bf16 v[20:23], v[224:227], v[182:185], v[20:23]
	s_addc_u32 s59, s59, 0
	v_mfma_f32_16x16x32_bf16 v[16:19], v[232:235], v[182:185], v[16:19]
	s_add_u32 s69, s69, 0x100
	v_mfma_f32_16x16x32_bf16 v[4:7], v[224:227], v[196:199], v[4:7]
	s_addc_u32 s70, s70, 0
	v_mfma_f32_16x16x32_bf16 v[0:3], v[232:235], v[196:199], v[0:3]
	s_cmp_gt_u32 s71, 13
	v_mfma_f32_16x16x32_bf16 v[52:55], v[228:231], v[164:167], v[52:55]
	v_mfma_f32_16x16x32_bf16 v[48:51], v[236:239], v[164:167], v[48:51]
	v_mfma_f32_16x16x32_bf16 v[36:39], v[228:231], v[172:175], v[36:39]
	v_mfma_f32_16x16x32_bf16 v[32:35], v[236:239], v[172:175], v[32:35]
	v_mfma_f32_16x16x32_bf16 v[20:23], v[228:231], v[186:189], v[20:23]
	v_mfma_f32_16x16x32_bf16 v[16:19], v[236:239], v[186:189], v[16:19]
	v_mfma_f32_16x16x32_bf16 v[4:7], v[228:231], v[200:203], v[4:7]
	v_mfma_f32_16x16x32_bf16 v[0:3], v[236:239], v[200:203], v[0:3]
	s_barrier
	s_setprio 0
	s_cbranch_scc0 .LBB0_557
	s_lshl_b32 s47, s54, 8
	s_add_i32 s47, s47, s57
	v_or_b32_e32 v162, s47, v192
	v_ashrrev_i32_e32 v163, 31, v162
	v_or_b32_e32 v190, 16, v162
	v_lshlrev_b64 v[80:81], 6, v[162:163]
	v_ashrrev_i32_e32 v191, 31, v190
	v_or_b32_e32 v188, 32, v162
	v_lshl_add_u64 v[80:81], v[154:155], 0, v[80:81]
	v_lshlrev_b64 v[82:83], 6, v[190:191]
	v_ashrrev_i32_e32 v189, 31, v188
	v_lshl_add_u64 v[82:83], v[154:155], 0, v[82:83]
	global_load_dwordx4 v[174:177], v[80:81], off
	global_load_dwordx4 v[196:199], v[82:83], off
	v_lshlrev_b64 v[80:81], 6, v[188:189]
	v_or_b32_e32 v186, 48, v162
	v_lshl_add_u64 v[80:81], v[154:155], 0, v[80:81]
	v_ashrrev_i32_e32 v187, 31, v186
	global_load_dwordx4 v[200:203], v[80:81], off
	v_lshlrev_b64 v[80:81], 6, v[186:187]
	v_lshl_add_u64 v[80:81], v[154:155], 0, v[80:81]
	v_add_u32_e32 v184, 0x80, v162
	global_load_dwordx4 v[224:227], v[80:81], off
	v_ashrrev_i32_e32 v185, 31, v184
	v_lshlrev_b64 v[80:81], 6, v[184:185]
	v_lshl_add_u64 v[80:81], v[154:155], 0, v[80:81]
	global_load_dwordx4 v[228:231], v[80:81], off
	v_add_u32_e32 v172, 0x90, v162
	v_ashrrev_i32_e32 v173, 31, v172
	v_lshlrev_b64 v[80:81], 6, v[172:173]
	v_lshl_add_u64 v[80:81], v[154:155], 0, v[80:81]
	global_load_dwordx4 v[232:235], v[80:81], off
	v_add_u32_e32 v168, 0xa0, v162
	v_ashrrev_i32_e32 v169, 31, v168
	v_lshlrev_b64 v[80:81], 6, v[168:169]
	v_lshl_add_u64 v[80:81], v[154:155], 0, v[80:81]
	global_load_dwordx4 v[236:239], v[80:81], off
	v_add_u32_e32 v164, 0xb0, v162
	v_ashrrev_i32_e32 v165, 31, v164
	v_lshlrev_b64 v[80:81], 6, v[164:165]
	s_cmpk_lt_u32 s47, 0x2000
	v_lshl_add_u64 v[80:81], v[154:155], 0, v[80:81]
	s_cselect_b32 s47, 1, 2
	global_load_dwordx4 v[240:243], v[80:81], off
	v_mov_b32_e32 v218, s47
	v_cmp_lt_i32_e32 vcc, s23, v162
	v_lshl_or_b32 v166, s55, 8, v194
	v_ashrrev_i32_e32 v167, 31, v166
	v_cndmask_b32_e32 v185, 0, v218, vcc
	v_mul_u32_u24_e32 v82, 0x7600, v185
	v_lshlrev_b32_e32 v96, 2, v82
	v_lshl_add_u64 v[80:81], s[44:45], 0, v[96:97]
	v_lshl_add_u64 v[106:107], v[166:167], 2, v[80:81]
	global_load_dwordx4 v[80:83], v[106:107], off offset:16
	global_load_dwordx4 v[88:91], v[106:107], off
	global_load_dwordx4 v[102:105], v[106:107], off offset:528
	s_nop 0
	global_load_dwordx4 v[106:109], v[106:107], off offset:512
	v_lshl_or_b32 v160, s55, 7, v194
	v_cmp_lt_i32_e32 vcc, s23, v190
	s_waitcnt vmcnt(0)
	v_add_f32_e32 v96, v174, v175
	v_add_f32_e32 v161, v176, v177
	v_add_f32_e32 v96, v96, v161
	v_add_f32_e32 v161, v196, v197
	v_add_f32_e32 v163, v198, v199
	v_add_f32_e32 v161, v161, v163
	v_add_f32_e32 v165, v200, v201
	v_add_f32_e32 v169, v202, v203
	v_add_f32_e32 v163, v165, v169
	v_mov_b32_e32 v169, v161
	v_add_f32_e32 v170, v224, v225
	v_add_f32_e32 v171, v226, v227
	v_add_f32_e32 v165, v170, v171
	v_mov_b32_e32 v170, v163
	v_permlane16_swap_b32_e32 v161, v169
	s_nop 0
	v_permlane16_swap_b32_e32 v163, v170
	v_add_f32_e32 v201, v161, v169
	v_add_f32_e32 v199, v163, v170
	v_add_f32_e32 v161, v228, v229
	v_add_f32_e32 v163, v230, v231
	v_add_f32_e32 v161, v161, v163
	v_mov_b32_e32 v163, v161
	s_nop 1
	v_permlane16_swap_b32_e32 v161, v163
	v_add_f32_e32 v191, v161, v163
	v_add_f32_e32 v161, v232, v233
	v_add_f32_e32 v163, v234, v235
	v_add_f32_e32 v161, v161, v163
	v_mov_b32_e32 v173, v96
	v_mov_b32_e32 v163, v161
	s_nop 0
	v_permlane16_swap_b32_e32 v96, v173
	v_permlane16_swap_b32_e32 v161, v163
	v_add_f32_e32 v96, v96, v173
	v_add_f32_e32 v187, v161, v163
	v_add_f32_e32 v161, v236, v237
	v_add_f32_e32 v163, v238, v239
	v_mov_b32_e32 v173, v96
	v_add_f32_e32 v161, v161, v163
	s_nop 0
	v_permlane32_swap_b32_e32 v96, v173
	v_mov_b32_e32 v163, v161
	v_add_f32_e32 v96, v96, v173
	s_nop 0
	v_permlane16_swap_b32_e32 v161, v163
	v_fmamk_f32 v96, v96, 0x3a800000, v207
	v_add_f32_e32 v169, v161, v163
	v_add_f32_e32 v161, v240, v241
	v_add_f32_e32 v163, v242, v243
	v_mov_b32_e32 v171, v165
	v_rsq_f32_e32 v96, v96
	v_add_f32_e32 v161, v161, v163
	v_permlane16_swap_b32_e32 v165, v171
	v_mov_b32_e32 v163, v161
	v_add_f32_e32 v197, v165, v171
	s_nop 0
	v_permlane16_swap_b32_e32 v161, v163
	v_mov_b64_e32 v[170:171], s[42:43]
	v_add_f32_e32 v163, v161, v163
	v_ashrrev_i32_e32 v161, 31, v160
	v_mad_i64_i32 v[170:171], s[54:55], v162, s31, v[170:171]
	v_lshl_add_u64 v[224:225], v[160:161], 1, v[170:171]
	v_pk_mul_f32 v[182:183], v[82:83], s[0:1] op_sel_hi:[1,0]
	v_pk_mul_f32 v[176:177], v[80:81], s[0:1] op_sel_hi:[1,0]
	v_pk_mul_f32 v[174:175], v[90:91], s[0:1] op_sel_hi:[1,0]
	v_pk_mul_f32 v[170:171], v[88:89], s[0:1] op_sel_hi:[1,0]
	v_mul_f32_e32 v226, 0xbfb8aa3b, v96
	v_pk_fma_f32 v[228:229], v[144:145], v[226:227], v[174:175] op_sel_hi:[1,0,1]
	v_pk_fma_f32 v[230:231], v[142:143], v[226:227], v[170:171] op_sel_hi:[1,0,1]
	v_pk_fma_f32 v[232:233], v[140:141], v[226:227], v[182:183] op_sel_hi:[1,0,1]
	v_pk_fma_f32 v[226:227], v[138:139], v[226:227], v[176:177] op_sel_hi:[1,0,1]
	v_exp_f32_e32 v230, v230
	v_exp_f32_e32 v226, v226
	v_exp_f32_e32 v231, v231
	v_exp_f32_e32 v227, v227
	v_exp_f32_e32 v232, v232
	v_exp_f32_e32 v233, v233
	v_exp_f32_e32 v228, v228
	v_exp_f32_e32 v229, v229
	v_pk_add_f32 v[230:231], v[230:231], 1.0 op_sel_hi:[1,0]
	v_pk_add_f32 v[232:233], v[232:233], 1.0 op_sel_hi:[1,0]
	v_pk_add_f32 v[226:227], v[226:227], 1.0 op_sel_hi:[1,0]
	v_pk_add_f32 v[228:229], v[228:229], 1.0 op_sel_hi:[1,0]
	v_rcp_f32_e32 v230, v230
	v_rcp_f32_e32 v226, v226
	v_rcp_f32_e32 v231, v231
	v_rcp_f32_e32 v227, v227
	v_rcp_f32_e32 v232, v232
	v_rcp_f32_e32 v233, v233
	v_rcp_f32_e32 v228, v228
	v_rcp_f32_e32 v229, v229
	v_pk_fma_f32 v[142:143], v[142:143], v[96:97], v[88:89] op_sel_hi:[1,0,1]
	v_pk_fma_f32 v[140:141], v[140:141], v[96:97], v[82:83] op_sel_hi:[1,0,1]
	v_pk_fma_f32 v[138:139], v[138:139], v[96:97], v[80:81] op_sel_hi:[1,0,1]
	v_pk_fma_f32 v[134:135], v[134:135], v[96:97], v[106:107] op_sel_hi:[1,0,1]
	v_pk_fma_f32 v[132:133], v[132:133], v[96:97], v[104:105] op_sel_hi:[1,0,1]
	v_pk_fma_f32 v[130:131], v[130:131], v[96:97], v[102:103] op_sel_hi:[1,0,1]
	v_pk_fma_f32 v[144:145], v[144:145], v[96:97], v[90:91] op_sel_hi:[1,0,1]
	v_pk_fma_f32 v[136:137], v[136:137], v[96:97], v[108:109] op_sel_hi:[1,0,1]
	v_pk_mul_f32 v[134:135], v[142:143], v[134:135]
	v_pk_mul_f32 v[132:133], v[140:141], v[132:133]
	v_pk_mul_f32 v[130:131], v[138:139], v[130:131]
	v_pk_mul_f32 v[136:137], v[144:145], v[136:137]
	v_pk_mul_f32 v[134:135], v[134:135], v[230:231]
	v_pk_mul_f32 v[138:139], v[132:133], v[232:233]
	v_pk_mul_f32 v[132:133], v[130:131], v[226:227]
	v_cvt_pk_bf16_f32 v130, v134, v135
	v_mov_b32_e32 v202, v201
	v_mov_b32_e32 v200, v199
	v_mov_b32_e32 v198, v197
	v_mov_b32_e32 v196, v191
	v_mov_b32_e32 v189, v187
	v_mov_b32_e32 v173, v169
	v_mov_b32_e32 v165, v163
	v_pk_mul_f32 v[136:137], v[136:137], v[228:229]
	v_permlane32_swap_b32_e32 v201, v202
	v_cvt_pk_bf16_f32 v131, v136, v137
	v_cvt_pk_bf16_f32 v132, v132, v133
	v_cvt_pk_bf16_f32 v133, v138, v139
	global_store_dwordx4 v[224:225], v[130:133], off
	v_permlane32_swap_b32_e32 v199, v200
	s_nop 0
	v_cndmask_b32_e32 v130, 0, v218, vcc
	v_permlane32_swap_b32_e32 v197, v198
	v_permlane32_swap_b32_e32 v191, v196
	v_permlane32_swap_b32_e32 v187, v189
	v_permlane32_swap_b32_e32 v169, v173
	v_permlane32_swap_b32_e32 v163, v165
	v_cmp_ne_u32_e32 vcc, v130, v185
	s_and_saveexec_b64 s[54:55], vcc
	s_cbranch_execz .LBB0_560
	v_mul_u32_u24_e32 v80, 0x7600, v130
	v_lshlrev_b32_e32 v96, 2, v80
	v_lshl_add_u64 v[80:81], s[44:45], 0, v[96:97]
	v_lshl_add_u64 v[106:107], v[166:167], 2, v[80:81]
	global_load_dwordx4 v[88:91], v[106:107], off
	global_load_dwordx4 v[80:83], v[106:107], off offset:16
	global_load_dwordx4 v[102:105], v[106:107], off offset:528
	s_nop 0
	global_load_dwordx4 v[106:109], v[106:107], off offset:512
	v_mov_b32_e32 v185, v130
	s_waitcnt vmcnt(0)
	v_pk_mul_f32 v[170:171], v[88:89], s[0:1] op_sel_hi:[1,0]
	v_pk_mul_f32 v[174:175], v[90:91], s[0:1] op_sel_hi:[1,0]
	v_pk_mul_f32 v[176:177], v[80:81], s[0:1] op_sel_hi:[1,0]
	v_pk_mul_f32 v[182:183], v[82:83], s[0:1] op_sel_hi:[1,0]

.LBB0_1021:
	s_add_i32 vcc_hi, s46, 2
	s_add_u32 s84, s44, 0x80
	s_addc_u32 s47, s45, 0
	s_add_i32 s29, 0, 0x10000
	v_add_u32_e32 v96, s29, v225
	ds_read_b128 v[56:59], v96
	ds_read_b128 v[68:71], v96 offset:1024
	ds_read_b128 v[80:83], v96 offset:2048
	ds_read_b128 v[98:101], v96 offset:3072
	s_cmp_eq_u32 s90, s46
	s_cselect_b32 s46, s80, s84
	s_cselect_b32 s47, s81, s47
	s_cselect_b32 s85, s83, vcc_lo
	s_cselect_b32 s84, s82, s87
	v_lshl_add_u64 v[106:107], s[44:45], 0, v[188:189]
	s_add_i32 m0, s2, 0xc000
	ds_read_b128 v[102:105], v227
	ds_read_b128 v[112:115], v227 offset:1024
	ds_read_b128 v[124:127], v227 offset:2048
	ds_read_b128 v[192:195], v227 offset:3072
	ds_read_b128 v[196:199], v227 offset:4096
	ds_read_b128 v[200:203], v227 offset:5120
	global_load_lds_dwordx4 v[106:107], off
	v_lshl_add_u64 v[106:107], s[44:45], 0, v[190:191]
	s_add_i32 m0, s2, 0xe000
	s_mov_b64 exec, s[98:99]
	global_load_lds_dwordx4 v[106:107], off
	s_mov_b64 exec, -1
	s_waitcnt lgkmcnt(8)
	s_setprio 1
	s_barrier
	s_waitcnt lgkmcnt(0)
	v_mfma_f32_16x16x32_bf16 v[172:175], v[56:59], v[102:105], v[172:175]
	v_mfma_f32_16x16x32_bf16 v[168:171], v[80:83], v[102:105], v[168:171]
	v_mfma_f32_16x16x32_bf16 v[156:159], v[56:59], v[124:127], v[156:159]
	v_mfma_f32_16x16x32_bf16 v[152:155], v[80:83], v[124:127], v[152:155]
	v_mfma_f32_16x16x32_bf16 v[132:135], v[56:59], v[196:199], v[132:135]
	v_mfma_f32_16x16x32_bf16 v[128:131], v[80:83], v[196:199], v[128:131]
	v_mfma_f32_16x16x32_bf16 v[172:175], v[68:71], v[112:115], v[172:175]
	v_mfma_f32_16x16x32_bf16 v[168:171], v[98:101], v[112:115], v[168:171]
	v_mfma_f32_16x16x32_bf16 v[156:159], v[68:71], v[192:195], v[156:159]
	v_mfma_f32_16x16x32_bf16 v[152:155], v[98:101], v[192:195], v[152:155]
	v_mfma_f32_16x16x32_bf16 v[132:135], v[68:71], v[200:203], v[132:135]
	v_mfma_f32_16x16x32_bf16 v[128:131], v[98:101], v[200:203], v[128:131]
	s_barrier
	s_setprio 0
	s_add_i32 s96, 0, 0x14000
	s_add_i32 s29, s29, s18
	v_add_u32_e32 v96, s96, v225
	v_lshl_add_u64 v[106:107], s[84:85], 0, v[182:183]
	s_mov_b32 m0, s29
	ds_read_b128 v[228:231], v96
	ds_read_b128 v[232:235], v96 offset:1024
	ds_read_b128 v[236:239], v96 offset:2048
	ds_read_b128 v[240:243], v96 offset:3072
	global_load_lds_dwordx4 v[106:107], off
	v_lshl_add_u64 v[248:249], s[84:85], 0, v[186:187]
	s_add_i32 m0, s29, 0x2000
	s_nop 0
	global_load_lds_dwordx4 v[248:249], off
	s_setprio 1
	s_barrier
	s_waitcnt lgkmcnt(0)
	v_mfma_f32_16x16x32_bf16 v[164:167], v[228:231], v[102:105], v[164:167]
	v_mfma_f32_16x16x32_bf16 v[102:105], v[236:239], v[102:105], v[160:163]
	v_mfma_f32_16x16x32_bf16 v[120:123], v[228:231], v[196:199], v[120:123]
	s_mov_b32 m0, s2
	v_mfma_f32_16x16x32_bf16 v[116:119], v[236:239], v[196:199], v[116:119]
	v_lshl_add_u64 v[250:251], s[46:47], 0, v[176:177]
	v_mfma_f32_16x16x32_bf16 v[164:167], v[232:235], v[112:115], v[164:167]
	v_mfma_f32_16x16x32_bf16 v[102:105], v[240:243], v[112:115], v[102:105]
	v_mfma_f32_16x16x32_bf16 v[112:115], v[228:231], v[124:127], v[148:151]
	v_mfma_f32_16x16x32_bf16 v[124:127], v[236:239], v[124:127], v[144:147]
	v_mfma_f32_16x16x32_bf16 v[120:123], v[232:235], v[200:203], v[120:123]
	v_mfma_f32_16x16x32_bf16 v[116:119], v[240:243], v[200:203], v[116:119]
	v_mfma_f32_16x16x32_bf16 v[112:115], v[232:235], v[192:195], v[112:115]
	v_mfma_f32_16x16x32_bf16 v[124:127], v[240:243], v[192:195], v[124:127]
	s_barrier
	s_setprio 0
	ds_read_b128 v[144:147], v227 offset:16384
	ds_read_b128 v[148:151], v227 offset:17408
	ds_read_b128 v[160:163], v227 offset:18432
	ds_read_b128 v[192:195], v227 offset:19456
	ds_read_b128 v[196:199], v227 offset:20480
	ds_read_b128 v[200:203], v227 offset:21504
	global_load_lds_dwordx4 v[250:251], off
	v_lshl_add_u64 v[252:253], s[46:47], 0, v[184:185]
	s_mov_b32 m0, s3
	s_mov_b64 exec, s[98:99]
	global_load_lds_dwordx4 v[252:253], off
	s_mov_b64 exec, -1
	s_setprio 1
	s_barrier
	s_waitcnt lgkmcnt(0)
	v_mfma_f32_16x16x32_bf16 v[88:91], v[56:59], v[144:147], v[88:91]
	v_mfma_f32_16x16x32_bf16 v[84:87], v[80:83], v[144:147], v[84:87]
	v_mfma_f32_16x16x32_bf16 v[52:55], v[56:59], v[160:163], v[52:55]
	v_mfma_f32_16x16x32_bf16 v[48:51], v[80:83], v[160:163], v[48:51]
	v_mfma_f32_16x16x32_bf16 v[28:31], v[56:59], v[196:199], v[28:31]
	v_mfma_f32_16x16x32_bf16 v[24:27], v[80:83], v[196:199], v[24:27]
	v_mfma_f32_16x16x32_bf16 v[88:91], v[68:71], v[148:151], v[88:91]
	v_mfma_f32_16x16x32_bf16 v[84:87], v[98:101], v[148:151], v[84:87]
	v_mfma_f32_16x16x32_bf16 v[52:55], v[68:71], v[192:195], v[52:55]
	v_mfma_f32_16x16x32_bf16 v[48:51], v[98:101], v[192:195], v[48:51]
	v_mfma_f32_16x16x32_bf16 v[28:31], v[68:71], v[200:203], v[28:31]
	v_mfma_f32_16x16x32_bf16 v[24:27], v[98:101], v[200:203], v[24:27]
	s_barrier
	s_setprio 0
	s_add_u32 s84, s84, s57
	s_addc_u32 s85, s85, 0
	s_add_i32 s29, s96, s18
	v_lshl_add_u64 v[218:219], s[84:85], 0, v[182:183]
	s_mov_b32 m0, s29
	v_lshl_add_u64 v[220:221], s[84:85], 0, v[186:187]
	global_load_lds_dwordx4 v[218:219], off
	s_add_i32 m0, s29, 0x2000
	s_nop 0
	global_load_lds_dwordx4 v[220:221], off
	s_waitcnt vmcnt(6)
	s_setprio 1
	s_barrier
	v_mfma_f32_16x16x32_bf16 v[44:47], v[228:231], v[160:163], v[44:47]
	v_mfma_f32_16x16x32_bf16 v[40:43], v[236:239], v[160:163], v[40:43]
	v_mfma_f32_16x16x32_bf16 v[20:23], v[228:231], v[196:199], v[20:23]
	s_add_i32 s29, 0, 0x18000
	v_mfma_f32_16x16x32_bf16 v[16:19], v[236:239], v[196:199], v[16:19]
	v_add_u32_e32 v96, s29, v225
	v_mfma_f32_16x16x32_bf16 v[56:59], v[228:231], v[144:147], v[76:79]
	v_mfma_f32_16x16x32_bf16 v[68:71], v[236:239], v[144:147], v[72:75]
	v_mfma_f32_16x16x32_bf16 v[44:47], v[232:235], v[192:195], v[44:47]
	v_mfma_f32_16x16x32_bf16 v[40:43], v[240:243], v[192:195], v[40:43]
	v_mfma_f32_16x16x32_bf16 v[20:23], v[232:235], v[200:203], v[20:23]
	v_mfma_f32_16x16x32_bf16 v[16:19], v[240:243], v[200:203], v[16:19]
	v_mfma_f32_16x16x32_bf16 v[56:59], v[232:235], v[148:151], v[56:59]
	v_mfma_f32_16x16x32_bf16 v[68:71], v[240:243], v[148:151], v[68:71]
	s_barrier
	s_setprio 0
	ds_read_b128 v[72:75], v96
	ds_read_b128 v[76:79], v96 offset:1024
	ds_read_b128 v[80:83], v96 offset:2048
	ds_read_b128 v[98:101], v96 offset:3072
	s_add_u32 s46, s46, s64
	s_addc_u32 s47, s47, 0
	s_mov_b32 m0, s4
	v_lshl_add_u64 v[160:161], s[46:47], 0, v[176:177]
	ds_read_b128 v[144:147], v227 offset:32768
	ds_read_b128 v[148:151], v227 offset:33792
	ds_read_b128 v[192:195], v227 offset:34816
	ds_read_b128 v[196:199], v227 offset:35840
	ds_read_b128 v[200:203], v227 offset:36864
	ds_read_b128 v[228:231], v227 offset:37888
	global_load_lds_dwordx4 v[160:161], off
	v_lshl_add_u64 v[160:161], s[46:47], 0, v[184:185]
	s_mov_b32 m0, s5
	s_mov_b64 exec, s[98:99]
	global_load_lds_dwordx4 v[160:161], off
	s_mov_b64 exec, -1
	s_waitcnt lgkmcnt(8)
	s_setprio 1
	s_barrier
	s_waitcnt lgkmcnt(0)
	v_mfma_f32_16x16x32_bf16 v[160:163], v[72:75], v[144:147], v[172:175]
	v_mfma_f32_16x16x32_bf16 v[172:175], v[76:79], v[148:151], v[160:163]
	v_mfma_f32_16x16x32_bf16 v[160:163], v[80:83], v[144:147], v[168:171]
	v_mfma_f32_16x16x32_bf16 v[156:159], v[72:75], v[192:195], v[156:159]
	v_mfma_f32_16x16x32_bf16 v[152:155], v[80:83], v[192:195], v[152:155]
	v_mfma_f32_16x16x32_bf16 v[132:135], v[72:75], v[200:203], v[132:135]
	v_mfma_f32_16x16x32_bf16 v[128:131], v[80:83], v[200:203], v[128:131]
	v_mfma_f32_16x16x32_bf16 v[168:171], v[98:101], v[148:151], v[160:163]
	v_mfma_f32_16x16x32_bf16 v[156:159], v[76:79], v[196:199], v[156:159]
	v_mfma_f32_16x16x32_bf16 v[152:155], v[98:101], v[196:199], v[152:155]
	v_mfma_f32_16x16x32_bf16 v[132:135], v[76:79], v[228:231], v[132:135]
	v_mfma_f32_16x16x32_bf16 v[128:131], v[98:101], v[228:231], v[128:131]
	s_barrier
	s_setprio 0
	s_add_i32 s46, 0, 0x1c000
	s_add_i32 s29, s29, s18
	v_add_u32_e32 v96, s46, v225
	v_lshl_add_u64 v[106:107], v[106:107], 0, s[6:7]
	s_mov_b32 m0, s29
	ds_read_b128 v[232:235], v96
	ds_read_b128 v[236:239], v96 offset:1024
	ds_read_b128 v[240:243], v96 offset:2048
	ds_read_b128 v[244:247], v96 offset:3072
	global_load_lds_dwordx4 v[106:107], off
	v_lshl_add_u64 v[106:107], v[248:249], 0, s[6:7]
	s_add_i32 m0, s29, 0x2000
	s_nop 0
	global_load_lds_dwordx4 v[106:107], off
	s_setprio 1
	s_barrier
	s_waitcnt lgkmcnt(0)
	v_mfma_f32_16x16x32_bf16 v[160:163], v[232:235], v[144:147], v[164:167]
	v_mfma_f32_16x16x32_bf16 v[102:105], v[240:243], v[144:147], v[102:105]
	v_mfma_f32_16x16x32_bf16 v[164:167], v[236:239], v[148:151], v[160:163]
	s_mov_b32 m0, s88
	v_mfma_f32_16x16x32_bf16 v[160:163], v[244:247], v[148:151], v[102:105]
	v_lshl_add_u64 v[106:107], v[250:251], 0, s[6:7]
	v_mfma_f32_16x16x32_bf16 v[102:105], v[232:235], v[192:195], v[112:115]
	v_mfma_f32_16x16x32_bf16 v[148:151], v[236:239], v[196:199], v[102:105]
	v_mfma_f32_16x16x32_bf16 v[102:105], v[240:243], v[192:195], v[124:127]
	v_mfma_f32_16x16x32_bf16 v[144:147], v[244:247], v[196:199], v[102:105]
	v_mfma_f32_16x16x32_bf16 v[102:105], v[232:235], v[200:203], v[120:123]
	v_mfma_f32_16x16x32_bf16 v[120:123], v[236:239], v[228:231], v[102:105]
	v_mfma_f32_16x16x32_bf16 v[102:105], v[240:243], v[200:203], v[116:119]
	v_mfma_f32_16x16x32_bf16 v[116:119], v[244:247], v[228:231], v[102:105]
	s_barrier
	s_setprio 0
	s_nop 2
	ds_read_b128 v[102:105], v227 offset:49152
	ds_read_b128 v[112:115], v227 offset:50176
	ds_read_b128 v[124:127], v227 offset:51200
	ds_read_b128 v[192:195], v227 offset:52224
	ds_read_b128 v[196:199], v227 offset:53248
	ds_read_b128 v[200:203], v227 offset:54272
	global_load_lds_dwordx4 v[106:107], off
	v_lshl_add_u64 v[106:107], v[252:253], 0, s[6:7]
	s_mov_b32 m0, s89
	s_mov_b64 exec, s[98:99]
	global_load_lds_dwordx4 v[106:107], off
	s_mov_b64 exec, -1
	s_setprio 1
	s_barrier
	s_waitcnt lgkmcnt(0)
	v_mfma_f32_16x16x32_bf16 v[88:91], v[72:75], v[102:105], v[88:91]
	v_mfma_f32_16x16x32_bf16 v[84:87], v[80:83], v[102:105], v[84:87]
	v_mfma_f32_16x16x32_bf16 v[52:55], v[72:75], v[124:127], v[52:55]
	v_mfma_f32_16x16x32_bf16 v[48:51], v[80:83], v[124:127], v[48:51]
	v_mfma_f32_16x16x32_bf16 v[28:31], v[72:75], v[196:199], v[28:31]
	v_mfma_f32_16x16x32_bf16 v[24:27], v[80:83], v[196:199], v[24:27]
	v_mfma_f32_16x16x32_bf16 v[88:91], v[76:79], v[112:115], v[88:91]
	v_mfma_f32_16x16x32_bf16 v[84:87], v[98:101], v[112:115], v[84:87]
	v_mfma_f32_16x16x32_bf16 v[52:55], v[76:79], v[192:195], v[52:55]
	v_mfma_f32_16x16x32_bf16 v[48:51], v[98:101], v[192:195], v[48:51]
	v_mfma_f32_16x16x32_bf16 v[28:31], v[76:79], v[200:203], v[28:31]
	v_mfma_f32_16x16x32_bf16 v[24:27], v[98:101], v[200:203], v[24:27]
	s_barrier
	s_setprio 0
	s_add_i32 s29, s46, s18
	v_lshl_add_u64 v[72:73], v[218:219], 0, s[6:7]
	s_mov_b32 m0, s29
	s_nop 0
	global_load_lds_dwordx4 v[72:73], off
	v_lshl_add_u64 v[72:73], v[220:221], 0, s[6:7]
	s_add_i32 m0, s29, 0x2000
	s_nop 0
	global_load_lds_dwordx4 v[72:73], off
	s_waitcnt vmcnt(6)
	s_setprio 1
	s_barrier
	v_mfma_f32_16x16x32_bf16 v[56:59], v[232:235], v[102:105], v[56:59]
	v_mfma_f32_16x16x32_bf16 v[76:79], v[236:239], v[112:115], v[56:59]
	v_mfma_f32_16x16x32_bf16 v[56:59], v[240:243], v[102:105], v[68:71]
	s_add_u32 s44, s44, 0x100
	v_mfma_f32_16x16x32_bf16 v[44:47], v[232:235], v[124:127], v[44:47]
	s_addc_u32 s45, s45, 0
	v_mfma_f32_16x16x32_bf16 v[40:43], v[240:243], v[124:127], v[40:43]
	s_add_u32 s87, s87, 0x100
	v_mfma_f32_16x16x32_bf16 v[20:23], v[232:235], v[196:199], v[20:23]
	s_addc_u32 vcc_lo, vcc_lo, 0
	v_mfma_f32_16x16x32_bf16 v[16:19], v[240:243], v[196:199], v[16:19]
	s_cmp_ge_u32 vcc_hi, s37
	v_mfma_f32_16x16x32_bf16 v[72:75], v[244:247], v[112:115], v[56:59]
	s_mov_b32 s46, vcc_hi
	v_mfma_f32_16x16x32_bf16 v[44:47], v[236:239], v[192:195], v[44:47]
	v_mfma_f32_16x16x32_bf16 v[40:43], v[244:247], v[192:195], v[40:43]
	v_mfma_f32_16x16x32_bf16 v[20:23], v[236:239], v[200:203], v[20:23]
	v_mfma_f32_16x16x32_bf16 v[16:19], v[244:247], v[200:203], v[16:19]
	s_barrier
	s_setprio 0
	s_cbranch_scc0 .LBB0_1021
	s_mul_i32 s44, s86, 0xc0
	s_add_i32 s44, s44, s19
	s_cmpk_lt_u32 s44, 0x2000
	v_or_b32_e32 v198, s44, v223
	s_cselect_b32 s44, 1, 2
	v_mov_b32_e32 v56, s44
	v_cmp_lt_i32_e32 vcc, s23, v198
	v_lshl_or_b32 v192, s72, 8, v226
	v_ashrrev_i32_e32 v193, 31, v192
	v_cndmask_b32_e32 v228, 0, v56, vcc
	v_mul_u32_u24_e32 v56, 0x1800, v228
	v_lshlrev_b32_e32 v96, 2, v56
	v_lshl_add_u64 v[56:57], s[70:71], 0, v[96:97]
	v_lshlrev_b64 v[68:69], 2, v[192:193]
	v_lshl_add_u64 v[124:125], v[56:57], 0, v[68:69]
	global_load_dwordx4 v[56:59], v[124:125], off
	v_cndmask_b32_e64 v70, 0, 1, s[78:79]
	v_cmp_ne_u32_e64 s[46:47], 1, v70
	s_andn2_b64 vcc, exec, s[78:79]
	v_lshl_add_u64 v[196:197], s[54:55], 0, v[68:69]
	s_cbranch_vccnz .LBB0_1024
	global_load_dwordx4 v[80:83], v[196:197], off
	s_waitcnt vmcnt(0)
	v_pk_mul_f32 v[58:59], v[58:59], v[82:83]
	v_pk_mul_f32 v[56:57], v[56:57], v[80:81]
